# lane-transposed (quad-coalesced) Z stores in in-proj epilogue
# speedup vs baseline: 1.0018x; 1.0018x over previous
;     __device__ __forceinline__ void operator()(AccT acc, const Unit& u, int wr, int wc, int fr, int fq) const {
;         const int col0 = u.pn * BM + wc * 32 + 8 * fq;
;         const bool uni = u.pm < NPROMPT / BM;
;         f32x4 sh[2][2] = {{(f32x4){0.f, 0.f, 0.f, 0.f}, (f32x4){0.f, 0.f, 0.f, 0.f}}, {(f32x4){0.f, 0.f, 0.f, 0.f}, (f32x4){0.f, 0.f, 0.f, 0.f}}};
;         if (uni) { const float* sw = SHW + (size_t)(u.pm >> 3) * NZT + col0;
; #pragma unroll
;             for (int bj = 0; bj < 2; ++bj) { sh[bj][0] = *(const f32x4*)(sw + bj * HALF); sh[bj][1] = *(const f32x4*)(sw + bj * HALF + 4); } }
;         float rs8[8];
; #pragma unroll
;         for (int r8 = 0; r8 < 8; ++r8) rs8[r8] = row_rs(SSQ, u.pm * BM + (r8 >> 2) * HALF + wr * 64 + (r8 & 3) * 16 + fr, fq);
;         const int side = (u.pn >= 6 && u.pn < 18) ? 1 : ((u.pn >= 22 && u.pn < 32) ? 2 : 0);
;         EPI_ROWS_BEGIN
;             const float rs = rs8[ai * 4 + m];
;             const int sq = seq_of_row(row); const bool isS = row >= NPROMPT; const int t = isS ? ((row - NPROMPT) & 7) : (row & (SEQ - 1));
.LBB0_658:
	v_mbcnt_lo_u32_b32 v232, -1, 0
	v_mbcnt_hi_u32_b32 v232, -1, v232
	v_and_b32_e32 v233, 3, v232
	v_lshrrev_b32_e32 v232, 2, v232
	v_lshl_add_u32 v232, v233, 4, v232
	v_lshlrev_b32_e32 v232, 2, v232
	s_cmpk_gt_i32 s6, 0x7f
	v_lshl_or_b32 v174, s18, 8, v186
	s_cselect_b64 s[8:9], -1, 0
	s_cmpk_lt_i32 s6, 0x80
	s_mov_b64 s[10:11], -1
	s_cbranch_scc1 .LBB0_660
	v_ashrrev_i32_e32 v175, 31, v174
	s_mov_b64 s[10:11], 0

; __device__ __forceinline__ unsigned cvt_pk_bf16(float lo, float hi) { unsigned r; asm volatile("v_cvt_pk_bf16_f32 %0, %1, %2" : "=v"(r) : "v"(lo), "v"(hi)); return r; }
;     __device__ __forceinline__ void operator()(AccT acc, const Unit& u, int wr, int wc, int fr, int fq) const {
;     ...
;             for (int bj = 0; bj < 2; ++bj) { const int c = col0 + bj * HALF;
;                 const f32x4 v0 = acc[ai][bj][m][0] * rs + sh[bj][0], v1 = acc[ai][bj][m][1] * rs + sh[bj][1];
;                 if (u.pn < 48) {
;                     u32x4 w; w.x = cvt_pk_bf16(v0[0], v0[1]); w.y = cvt_pk_bf16(v0[2], v0[3]); w.z = cvt_pk_bf16(v1[0], v1[1]); w.w = cvt_pk_bf16(v1[2], v1[3]);
;                     *(u32x4*)ZP(Z, row, c) = w;
;                     if (side) {
;                         float* dst = nullptr;
;                         if (side == 1) {
;                             const int kv = c >= ZV ? 1 : 0, cc = c - (kv ? ZV : ZK), g = cc >> 9, ci = cc & 511; const int keep = g == 0 ? 128 : (g == 1 ? 512 : 2048);
;                             if (isS) dst = out + (g == 0 ? O_SKV1 : (g == 1 ? O_SKV2 : O_SKV3)) + ((size_t)(l * 32 + (sq - 16)) * 8 + t) * 1024 + kv * 512 + ci;
;                             else if (t >= SEQ - keep) dst = out + (g == 0 ? O_PKV1 : (g == 1 ? O_PKV2 : O_PKV3)) + ((size_t)(l * 16 + sq) * keep + (t - (SEQ - keep))) * 1024 + kv * 512 + ci;
.LBB0_700:
	v_and_b32_e32 v226, 0x7cf, v176
	v_mad_i64_i32 v[146:147], s[14:15], s18, v195, v[176:177]
	v_cndmask_b32_e64 v148, v226, v161, s[12:13]
	v_lshlrev_b64 v[146:147], 9, v[146:147]
	v_cndmask_b32_e64 v149, v196, 5, s[12:13]
	v_sub_co_u32_e32 v158, vcc, v148, v149
	v_lshl_add_u64 v[148:149], s[22:23], 0, v[146:147]
	v_and_b32_e32 v146, 0x78, v174
	s_xor_b64 s[58:59], vcc, -1
	s_andn2_b64 vcc, exec, s[8:9]
	v_lshlrev_b32_e32 v146, 1, v146
	s_cbranch_vccnz .LBB0_713
	v_mov_b32_e32 v147, v159
	v_lshl_add_u64 v[228:229], v[148:149], 0, v[146:147]
	s_cmp_lt_i32 s47, 1
	v_cvt_pk_bf16_f32 v182, v142, v143
	v_cvt_pk_bf16_f32 v183, v144, v145
	v_cvt_pk_bf16_f32 v184, v138, v139
	v_cvt_pk_bf16_f32 v185, v140, v141
	ds_bpermute_b32 v234, v232, v228
	ds_bpermute_b32 v235, v232, v229
	ds_bpermute_b32 v236, v232, v182
	ds_bpermute_b32 v237, v232, v183
	ds_bpermute_b32 v238, v232, v184
	ds_bpermute_b32 v239, v232, v185
	s_waitcnt lgkmcnt(0)
	global_store_dwordx4 v[234:235], v[236:239], off
	s_cbranch_scc1 .LBB0_713
	s_cmp_lg_u32 s47, 1
	s_mov_b64 s[8:9], -1
	s_cbranch_scc0 .LBB0_1178
	v_mov_b64_e32 v[182:183], 0
	s_and_saveexec_b64 s[8:9], s[58:59]
	s_cbranch_execz .LBB0_709
	v_mov_b32_e32 v147, s56
	v_cndmask_b32_e64 v147, v147, v178, s[12:13]
	v_lshl_add_u32 v182, v147, 1, v147
	v_ashrrev_i32_e32 v183, 31, v182
	v_cmp_lt_i32_e32 vcc, s26, v174
	v_lshl_add_u64 v[184:185], v[182:183], 0, v[158:159]
	s_and_saveexec_b64 s[14:15], vcc
	s_xor_b64 s[14:15], exec, s[14:15]
	s_cbranch_execz .LBB0_706
	v_lshlrev_b64 v[184:185], 12, v[184:185]
	v_cndmask_b32_e64 v182, v197, v198, s[12:13]
	v_mov_b32_e32 v183, v159
	v_lshl_add_u64 v[184:185], s[24:25], 0, v[184:185]
	v_lshl_add_u64 v[182:183], v[184:185], 0, v[182:183]
	v_mov_b32_e32 v184, v174
	v_mov_b32_e32 v185, v159
	s_movk_i32 s16, 0x9000
	v_lshl_add_u64 v[182:183], v[184:185], 2, v[182:183]
	s_mov_b32 s17, -1
	v_lshl_add_u64 v[182:183], v[182:183], 0, s[16:17]

; __device__ __forceinline__ unsigned cvt_pk_bf16(float lo, float hi) { unsigned r; asm volatile("v_cvt_pk_bf16_f32 %0, %1, %2" : "=v"(r) : "v"(lo), "v"(hi)); return r; }
;     __device__ __forceinline__ void operator()(AccT acc, const Unit& u, int wr, int wc, int fr, int fq) const {
;     ...
;             for (int bj = 0; bj < 2; ++bj) { const int c = col0 + bj * HALF;
;                 const f32x4 v0 = acc[ai][bj][m][0] * rs + sh[bj][0], v1 = acc[ai][bj][m][1] * rs + sh[bj][1];
;                 if (u.pn < 48) {
;                     u32x4 w; w.x = cvt_pk_bf16(v0[0], v0[1]); w.y = cvt_pk_bf16(v0[2], v0[3]); w.z = cvt_pk_bf16(v1[0], v1[1]); w.w = cvt_pk_bf16(v1[2], v1[3]);
;                     *(u32x4*)ZP(Z, row, c) = w;
.LBB0_713:
	v_or_b32_e32 v144, 0x80, v174
	v_cndmask_b32_e64 v138, 0, 1, s[54:55]
	v_cmp_ne_u32_e64 s[8:9], 1, v138
	v_and_b32_e32 v138, 0xf8, v144
	s_andn2_b64 vcc, exec, s[54:55]
	v_lshlrev_b32_e32 v138, 1, v138
	s_cbranch_vccnz .LBB0_726
	v_mov_b32_e32 v181, v180
	v_mov_b32_e32 v140, v180
	v_mov_b32_e32 v141, v180
	v_mov_b32_e32 v139, v159
	v_pk_fma_f32 v[136:137], v[136:137], v[140:141], v[16:17]
	v_pk_fma_f32 v[134:135], v[134:135], v[180:181], v[14:15]
	v_pk_fma_f32 v[132:133], v[132:133], v[140:141], v[12:13]
	v_pk_fma_f32 v[130:131], v[130:131], v[180:181], v[10:11]
	v_lshl_add_u64 v[148:149], v[148:149], 0, v[138:139]
	s_cmp_lt_i32 s47, 1
	v_cvt_pk_bf16_f32 v140, v134, v135
	v_cvt_pk_bf16_f32 v141, v136, v137
	v_cvt_pk_bf16_f32 v142, v130, v131
	v_cvt_pk_bf16_f32 v143, v132, v133
	ds_bpermute_b32 v234, v232, v148
	ds_bpermute_b32 v235, v232, v149
	ds_bpermute_b32 v236, v232, v140
	ds_bpermute_b32 v237, v232, v141
	ds_bpermute_b32 v238, v232, v142
	ds_bpermute_b32 v239, v232, v143
	s_waitcnt lgkmcnt(0)
	global_store_dwordx4 v[234:235], v[236:239], off
	s_cbranch_scc1 .LBB0_726
	s_cmp_lg_u32 s47, 1
	s_mov_b64 s[14:15], -1
	s_cbranch_scc0 .LBB0_1186
	v_mov_b64_e32 v[140:141], 0
	s_and_saveexec_b64 s[14:15], s[58:59]
	s_cbranch_execz .LBB0_722
	v_mov_b32_e32 v139, s56
	v_cndmask_b32_e64 v139, v139, v178, s[12:13]
	v_lshl_add_u32 v140, v139, 1, v139
	v_ashrrev_i32_e32 v141, 31, v140
	v_cmp_lt_i32_e32 vcc, s26, v144
	v_lshl_add_u64 v[142:143], v[140:141], 0, v[158:159]
	s_and_saveexec_b64 s[16:17], vcc
	s_xor_b64 s[16:17], exec, s[16:17]
	v_lshlrev_b64 v[140:141], 12, v[142:143]
	v_cndmask_b32_e64 v158, v197, v198, s[12:13]
	v_lshl_add_u64 v[140:141], s[24:25], 0, v[140:141]
	v_lshl_add_u64 v[140:141], v[140:141], 0, v[158:159]
	v_mov_b32_e32 v158, v174
	v_lshl_add_u64 v[140:141], v[158:159], 2, v[140:141]
	v_lshl_add_u64 v[140:141], v[140:141], 0, s[42:43]
	s_andn2_saveexec_b64 s[16:17], s[16:17]
	v_mov_b64_e32 v[140:141], s[24:25]
	v_cndmask_b32_e64 v158, v199, v200, s[12:13]
	v_mad_u64_u32 v[140:141], s[12:13], v142, s27, v[140:141]
	v_mad_i32_i24 v141, v143, s27, v141
	v_lshl_add_u64 v[140:141], v[140:141], 0, v[158:159]
	v_ashrrev_i32_e32 v143, 31, v174
	v_mov_b32_e32 v142, v174
	v_lshl_add_u64 v[140:141], v[142:143], 2, v[140:141]
	v_lshl_add_u64 v[140:141], v[140:141], 0, s[44:45]
	s_or_b64 exec, exec, s[16:17]

; __device__ __forceinline__ unsigned cvt_pk_bf16(float lo, float hi) { unsigned r; asm volatile("v_cvt_pk_bf16_f32 %0, %1, %2" : "=v"(r) : "v"(lo), "v"(hi)); return r; }
;     __device__ __forceinline__ void operator()(AccT acc, const Unit& u, int wr, int wc, int fr, int fq) const {
;     ...
;             const int sq = seq_of_row(row); const bool isS = row >= NPROMPT; const int t = isS ? ((row - NPROMPT) & 7) : (row & (SEQ - 1));
;             if (!uni) { const float* sw = SHW + (size_t)sq * NZT + col0;
; #pragma unroll
;                 for (int bj = 0; bj < 2; ++bj) { sh[bj][0] = *(const f32x4*)(sw + bj * HALF); sh[bj][1] = *(const f32x4*)(sw + bj * HALF + 4); }
;                 asm volatile("" :: "v"(sh[0][0]), "v"(sh[0][1]), "v"(sh[1][0]), "v"(sh[1][1])); }
; #pragma unroll
;             for (int bj = 0; bj < 2; ++bj) { const int c = col0 + bj * HALF;
;                 const f32x4 v0 = acc[ai][bj][m][0] * rs + sh[bj][0], v1 = acc[ai][bj][m][1] * rs + sh[bj][1];
;                 if (u.pn < 48) {
;                     u32x4 w; w.x = cvt_pk_bf16(v0[0], v0[1]); w.y = cvt_pk_bf16(v0[2], v0[3]); w.z = cvt_pk_bf16(v1[0], v1[1]); w.w = cvt_pk_bf16(v1[2], v1[3]);
;                     *(u32x4*)ZP(Z, row, c) = w;
;                     if (side) {
;                         float* dst = nullptr;
;                         if (side == 1) {
;                             const int kv = c >= ZV ? 1 : 0, cc = c - (kv ? ZV : ZK), g = cc >> 9, ci = cc & 511; const int keep = g == 0 ? 128 : (g == 1 ? 512 : 2048);
;                             if (isS) dst = out + (g == 0 ? O_SKV1 : (g == 1 ? O_SKV2 : O_SKV3)) + ((size_t)(l * 32 + (sq - 16)) * 8 + t) * 1024 + kv * 512 + ci;
;                             else if (t >= SEQ - keep) dst = out + (g == 0 ? O_PKV1 : (g == 1 ? O_PKV2 : O_PKV3)) + ((size_t)(l * 16 + sq) * keep + (t - (SEQ - keep))) * 1024 + kv * 512 + ci;
.LBB0_764:
	s_mul_hi_i32 s55, s18, 0x8100
	s_mul_i32 s54, s18, 0x8100
	v_and_b32_e32 v142, 0x7df, v140
	v_cndmask_b32_e64 v132, v142, v161, s[14:15]
	v_lshl_add_u64 v[130:131], s[54:55], 0, v[140:141]
	v_cndmask_b32_e64 v133, v196, 5, s[14:15]
	v_lshlrev_b64 v[130:131], 9, v[130:131]
	v_sub_co_u32_e32 v158, vcc, v132, v133
	s_xor_b64 s[58:59], vcc, -1
	s_andn2_b64 vcc, exec, s[16:17]
	v_lshl_add_u64 v[130:131], s[22:23], 0, v[130:131]
	s_cbranch_vccnz .LBB0_777
	v_mov_b32_e32 v147, v159
	v_lshl_add_u64 v[132:133], v[130:131], 0, v[146:147]
	s_cmp_lt_i32 s47, 1
	v_cvt_pk_bf16_f32 v178, v126, v127
	v_cvt_pk_bf16_f32 v179, v128, v129
	v_cvt_pk_bf16_f32 v180, v122, v123
	v_cvt_pk_bf16_f32 v181, v124, v125
	ds_bpermute_b32 v234, v232, v132
	ds_bpermute_b32 v235, v232, v133
	ds_bpermute_b32 v236, v232, v178
	ds_bpermute_b32 v237, v232, v179
	ds_bpermute_b32 v238, v232, v180
	ds_bpermute_b32 v239, v232, v181
	s_waitcnt lgkmcnt(0)
	global_store_dwordx4 v[234:235], v[236:239], off
	s_cbranch_scc1 .LBB0_777
	s_cmp_lg_u32 s47, 1
	s_mov_b64 s[16:17], -1
	s_cbranch_scc0 .LBB0_1194
	v_mov_b64_e32 v[132:133], 0
	s_and_saveexec_b64 s[16:17], s[58:59]
	s_cbranch_execz .LBB0_773
	v_mov_b32_e32 v132, s56
	v_cndmask_b32_e64 v132, v132, v134, s[14:15]
	v_lshl_add_u32 v132, v132, 1, v132
	v_ashrrev_i32_e32 v133, 31, v132
	v_cmp_lt_i32_e32 vcc, s26, v174
	v_lshl_add_u64 v[140:141], v[132:133], 0, v[158:159]
	s_and_saveexec_b64 s[18:19], vcc
	s_xor_b64 s[18:19], exec, s[18:19]
	s_cbranch_execz .LBB0_770
	v_lshlrev_b64 v[140:141], 12, v[140:141]
	v_cndmask_b32_e64 v132, v197, v198, s[14:15]
	v_mov_b32_e32 v133, v159
	v_lshl_add_u64 v[140:141], s[24:25], 0, v[140:141]
	v_lshl_add_u64 v[132:133], v[140:141], 0, v[132:133]
	v_mov_b32_e32 v140, v174
	v_mov_b32_e32 v141, v159
	s_movk_i32 s20, 0x9000
	v_lshl_add_u64 v[132:133], v[140:141], 2, v[132:133]
	s_mov_b32 s21, -1
	v_lshl_add_u64 v[132:133], v[132:133], 0, s[20:21]

; __device__ __forceinline__ unsigned cvt_pk_bf16(float lo, float hi) { unsigned r; asm volatile("v_cvt_pk_bf16_f32 %0, %1, %2" : "=v"(r) : "v"(lo), "v"(hi)); return r; }
;     __device__ __forceinline__ void operator()(AccT acc, const Unit& u, int wr, int wc, int fr, int fq) const {
;     ...
;             for (int bj = 0; bj < 2; ++bj) { const int c = col0 + bj * HALF;
;                 const f32x4 v0 = acc[ai][bj][m][0] * rs + sh[bj][0], v1 = acc[ai][bj][m][1] * rs + sh[bj][1];
;                 if (u.pn < 48) {
;                     u32x4 w; w.x = cvt_pk_bf16(v0[0], v0[1]); w.y = cvt_pk_bf16(v0[2], v0[3]); w.z = cvt_pk_bf16(v1[0], v1[1]); w.w = cvt_pk_bf16(v1[2], v1[3]);
;                     *(u32x4*)ZP(Z, row, c) = w;
;                     if (side) {
;                         float* dst = nullptr;
;                         if (side == 1) {
;                             const int kv = c >= ZV ? 1 : 0, cc = c - (kv ? ZV : ZK), g = cc >> 9, ci = cc & 511; const int keep = g == 0 ? 128 : (g == 1 ? 512 : 2048);
;                             if (isS) dst = out + (g == 0 ? O_SKV1 : (g == 1 ? O_SKV2 : O_SKV3)) + ((size_t)(l * 32 + (sq - 16)) * 8 + t) * 1024 + kv * 512 + ci;
;                             else if (t >= SEQ - keep) dst = out + (g == 0 ? O_PKV1 : (g == 1 ? O_PKV2 : O_PKV3)) + ((size_t)(l * 16 + sq) * keep + (t - (SEQ - keep))) * 1024 + kv * 512 + ci;
.LBB0_777:
	s_and_b64 vcc, exec, s[8:9]
	s_cbranch_vccnz .LBB0_790
	v_mov_b32_e32 v137, v136
	v_mov_b32_e32 v122, v136
	v_mov_b32_e32 v123, v136
	v_mov_b32_e32 v139, v159
	v_pk_fma_f32 v[120:121], v[120:121], v[122:123], v[16:17]
	v_pk_fma_f32 v[118:119], v[118:119], v[136:137], v[14:15]
	v_pk_fma_f32 v[116:117], v[116:117], v[122:123], v[12:13]
	v_pk_fma_f32 v[114:115], v[114:115], v[136:137], v[10:11]
	v_lshl_add_u64 v[126:127], v[130:131], 0, v[138:139]
	s_cmp_lt_i32 s47, 1
	v_cvt_pk_bf16_f32 v122, v118, v119
	v_cvt_pk_bf16_f32 v123, v120, v121
	v_cvt_pk_bf16_f32 v124, v114, v115
	v_cvt_pk_bf16_f32 v125, v116, v117
	ds_bpermute_b32 v234, v232, v126
	ds_bpermute_b32 v235, v232, v127
	ds_bpermute_b32 v236, v232, v122
	ds_bpermute_b32 v237, v232, v123
	ds_bpermute_b32 v238, v232, v124
	ds_bpermute_b32 v239, v232, v125
	s_waitcnt lgkmcnt(0)
	global_store_dwordx4 v[234:235], v[236:239], off
	s_cbranch_scc1 .LBB0_790
	s_cmp_lg_u32 s47, 1
	s_mov_b64 s[16:17], -1
	s_cbranch_scc0 .LBB0_1202
	v_mov_b64_e32 v[122:123], 0
	s_and_saveexec_b64 s[16:17], s[58:59]
	s_cbranch_execz .LBB0_786
	v_mov_b32_e32 v122, s56
	v_cndmask_b32_e64 v122, v122, v134, s[14:15]
	v_lshl_add_u32 v122, v122, 1, v122
	v_ashrrev_i32_e32 v123, 31, v122
	v_cmp_lt_i32_e32 vcc, s26, v144
	v_lshl_add_u64 v[124:125], v[122:123], 0, v[158:159]
	s_and_saveexec_b64 s[18:19], vcc
	s_xor_b64 s[18:19], exec, s[18:19]
	v_lshlrev_b64 v[122:123], 12, v[124:125]
	v_cndmask_b32_e64 v158, v197, v198, s[14:15]
	v_lshl_add_u64 v[122:123], s[24:25], 0, v[122:123]
	v_lshl_add_u64 v[122:123], v[122:123], 0, v[158:159]
	v_mov_b32_e32 v158, v174
	v_lshl_add_u64 v[122:123], v[158:159], 2, v[122:123]
	v_lshl_add_u64 v[122:123], v[122:123], 0, s[42:43]
	s_andn2_saveexec_b64 s[18:19], s[18:19]
	v_mov_b64_e32 v[122:123], s[24:25]
	v_cndmask_b32_e64 v158, v199, v200, s[14:15]
	v_mad_u64_u32 v[122:123], s[14:15], v124, s27, v[122:123]
	v_mad_i32_i24 v123, v125, s27, v123
	v_lshl_add_u64 v[122:123], v[122:123], 0, v[158:159]
	v_ashrrev_i32_e32 v125, 31, v174
	v_mov_b32_e32 v124, v174
	v_lshl_add_u64 v[122:123], v[124:125], 2, v[122:123]
	v_lshl_add_u64 v[122:123], v[122:123], 0, s[44:45]
	s_or_b64 exec, exec, s[18:19]

; __device__ __forceinline__ unsigned cvt_pk_bf16(float lo, float hi) { unsigned r; asm volatile("v_cvt_pk_bf16_f32 %0, %1, %2" : "=v"(r) : "v"(lo), "v"(hi)); return r; }
;     __device__ __forceinline__ void operator()(AccT acc, const Unit& u, int wr, int wc, int fr, int fq) const {
;     ...
;             const int sq = seq_of_row(row); const bool isS = row >= NPROMPT; const int t = isS ? ((row - NPROMPT) & 7) : (row & (SEQ - 1));
;             if (!uni) { const float* sw = SHW + (size_t)sq * NZT + col0;
; #pragma unroll
;                 for (int bj = 0; bj < 2; ++bj) { sh[bj][0] = *(const f32x4*)(sw + bj * HALF); sh[bj][1] = *(const f32x4*)(sw + bj * HALF + 4); }
;                 asm volatile("" :: "v"(sh[0][0]), "v"(sh[0][1]), "v"(sh[1][0]), "v"(sh[1][1])); }
; #pragma unroll
;             for (int bj = 0; bj < 2; ++bj) { const int c = col0 + bj * HALF;
;                 const f32x4 v0 = acc[ai][bj][m][0] * rs + sh[bj][0], v1 = acc[ai][bj][m][1] * rs + sh[bj][1];
;                 if (u.pn < 48) {
;                     u32x4 w; w.x = cvt_pk_bf16(v0[0], v0[1]); w.y = cvt_pk_bf16(v0[2], v0[3]); w.z = cvt_pk_bf16(v1[0], v1[1]); w.w = cvt_pk_bf16(v1[2], v1[3]);
;                     *(u32x4*)ZP(Z, row, c) = w;
;                     if (side) {
;                         float* dst = nullptr;
;                         if (side == 1) {
;                             const int kv = c >= ZV ? 1 : 0, cc = c - (kv ? ZV : ZK), g = cc >> 9, ci = cc & 511; const int keep = g == 0 ? 128 : (g == 1 ? 512 : 2048);
;                             if (isS) dst = out + (g == 0 ? O_SKV1 : (g == 1 ? O_SKV2 : O_SKV3)) + ((size_t)(l * 32 + (sq - 16)) * 8 + t) * 1024 + kv * 512 + ci;
;                             else if (t >= SEQ - keep) dst = out + (g == 0 ? O_PKV1 : (g == 1 ? O_PKV2 : O_PKV3)) + ((size_t)(l * 16 + sq) * keep + (t - (SEQ - keep))) * 1024 + kv * 512 + ci;
.LBB0_828:
	v_and_b32_e32 v124, 0x7ef, v122
	v_cndmask_b32_e64 v116, v124, v161, s[14:15]
	v_lshl_add_u64 v[114:115], s[54:55], 0, v[122:123]
	v_cndmask_b32_e64 v117, v196, 5, s[14:15]
	v_lshlrev_b64 v[114:115], 9, v[114:115]
	v_sub_co_u32_e32 v158, vcc, v116, v117
	s_xor_b64 s[58:59], vcc, -1
	s_andn2_b64 vcc, exec, s[16:17]
	v_lshl_add_u64 v[114:115], s[22:23], 0, v[114:115]
	s_cbranch_vccnz .LBB0_841
	v_mov_b32_e32 v147, v159
	v_lshl_add_u64 v[116:117], v[114:115], 0, v[146:147]
	s_cmp_lt_i32 s47, 1
	v_cvt_pk_bf16_f32 v126, v110, v111
	v_cvt_pk_bf16_f32 v127, v112, v113
	v_cvt_pk_bf16_f32 v128, v106, v107
	v_cvt_pk_bf16_f32 v129, v108, v109
	ds_bpermute_b32 v234, v232, v116
	ds_bpermute_b32 v235, v232, v117
	ds_bpermute_b32 v236, v232, v126
	ds_bpermute_b32 v237, v232, v127
	ds_bpermute_b32 v238, v232, v128
	ds_bpermute_b32 v239, v232, v129
	s_waitcnt lgkmcnt(0)
	global_store_dwordx4 v[234:235], v[236:239], off
	s_cbranch_scc1 .LBB0_841
	s_cmp_lg_u32 s47, 1
	s_mov_b64 s[16:17], -1
	s_cbranch_scc0 .LBB0_1210
	v_mov_b64_e32 v[116:117], 0
	s_and_saveexec_b64 s[16:17], s[58:59]
	s_cbranch_execz .LBB0_837
	v_mov_b32_e32 v116, s56
	v_cndmask_b32_e64 v116, v116, v118, s[14:15]
	v_lshl_add_u32 v116, v116, 1, v116
	v_ashrrev_i32_e32 v117, 31, v116
	v_cmp_lt_i32_e32 vcc, s26, v174
	v_lshl_add_u64 v[122:123], v[116:117], 0, v[158:159]
	s_and_saveexec_b64 s[18:19], vcc
	s_xor_b64 s[18:19], exec, s[18:19]
	s_cbranch_execz .LBB0_834
	v_lshlrev_b64 v[122:123], 12, v[122:123]
	v_cndmask_b32_e64 v116, v197, v198, s[14:15]
	v_mov_b32_e32 v117, v159
	v_lshl_add_u64 v[122:123], s[24:25], 0, v[122:123]
	v_lshl_add_u64 v[116:117], v[122:123], 0, v[116:117]
	v_mov_b32_e32 v122, v174
	v_mov_b32_e32 v123, v159
	s_movk_i32 s20, 0x9000
	v_lshl_add_u64 v[116:117], v[122:123], 2, v[116:117]
	s_mov_b32 s21, -1
	v_lshl_add_u64 v[116:117], v[116:117], 0, s[20:21]

; __device__ __forceinline__ unsigned cvt_pk_bf16(float lo, float hi) { unsigned r; asm volatile("v_cvt_pk_bf16_f32 %0, %1, %2" : "=v"(r) : "v"(lo), "v"(hi)); return r; }
;     __device__ __forceinline__ void operator()(AccT acc, const Unit& u, int wr, int wc, int fr, int fq) const {
;     ...
;             for (int bj = 0; bj < 2; ++bj) { const int c = col0 + bj * HALF;
;                 const f32x4 v0 = acc[ai][bj][m][0] * rs + sh[bj][0], v1 = acc[ai][bj][m][1] * rs + sh[bj][1];
;                 if (u.pn < 48) {
;                     u32x4 w; w.x = cvt_pk_bf16(v0[0], v0[1]); w.y = cvt_pk_bf16(v0[2], v0[3]); w.z = cvt_pk_bf16(v1[0], v1[1]); w.w = cvt_pk_bf16(v1[2], v1[3]);
;                     *(u32x4*)ZP(Z, row, c) = w;
;                     if (side) {
;                         float* dst = nullptr;
;                         if (side == 1) {
;                             const int kv = c >= ZV ? 1 : 0, cc = c - (kv ? ZV : ZK), g = cc >> 9, ci = cc & 511; const int keep = g == 0 ? 128 : (g == 1 ? 512 : 2048);
;                             if (isS) dst = out + (g == 0 ? O_SKV1 : (g == 1 ? O_SKV2 : O_SKV3)) + ((size_t)(l * 32 + (sq - 16)) * 8 + t) * 1024 + kv * 512 + ci;
;                             else if (t >= SEQ - keep) dst = out + (g == 0 ? O_PKV1 : (g == 1 ? O_PKV2 : O_PKV3)) + ((size_t)(l * 16 + sq) * keep + (t - (SEQ - keep))) * 1024 + kv * 512 + ci;
.LBB0_841:
	s_and_b64 vcc, exec, s[8:9]
	s_cbranch_vccnz .LBB0_854
	v_mov_b32_e32 v121, v120
	v_mov_b32_e32 v106, v120
	v_mov_b32_e32 v107, v120
	v_mov_b32_e32 v139, v159
	v_pk_fma_f32 v[104:105], v[104:105], v[106:107], v[16:17]
	v_pk_fma_f32 v[102:103], v[102:103], v[120:121], v[14:15]
	v_pk_fma_f32 v[100:101], v[100:101], v[106:107], v[12:13]
	v_pk_fma_f32 v[98:99], v[98:99], v[120:121], v[10:11]
	v_lshl_add_u64 v[110:111], v[114:115], 0, v[138:139]
	s_cmp_lt_i32 s47, 1
	v_cvt_pk_bf16_f32 v106, v102, v103
	v_cvt_pk_bf16_f32 v107, v104, v105
	v_cvt_pk_bf16_f32 v108, v98, v99
	v_cvt_pk_bf16_f32 v109, v100, v101
	ds_bpermute_b32 v234, v232, v110
	ds_bpermute_b32 v235, v232, v111
	ds_bpermute_b32 v236, v232, v106
	ds_bpermute_b32 v237, v232, v107
	ds_bpermute_b32 v238, v232, v108
	ds_bpermute_b32 v239, v232, v109
	s_waitcnt lgkmcnt(0)
	global_store_dwordx4 v[234:235], v[236:239], off
	s_cbranch_scc1 .LBB0_854
	s_cmp_lg_u32 s47, 1
	s_mov_b64 s[16:17], -1
	s_cbranch_scc0 .LBB0_1218
	v_mov_b64_e32 v[106:107], 0
	s_and_saveexec_b64 s[16:17], s[58:59]
	s_cbranch_execz .LBB0_850
	v_mov_b32_e32 v106, s56
	v_cndmask_b32_e64 v106, v106, v118, s[14:15]
	v_lshl_add_u32 v106, v106, 1, v106
	v_ashrrev_i32_e32 v107, 31, v106
	v_cmp_lt_i32_e32 vcc, s26, v144
	v_lshl_add_u64 v[108:109], v[106:107], 0, v[158:159]
	s_and_saveexec_b64 s[18:19], vcc
	s_xor_b64 s[18:19], exec, s[18:19]
	v_lshlrev_b64 v[106:107], 12, v[108:109]
	v_cndmask_b32_e64 v158, v197, v198, s[14:15]
	v_lshl_add_u64 v[106:107], s[24:25], 0, v[106:107]
	v_lshl_add_u64 v[106:107], v[106:107], 0, v[158:159]
	v_mov_b32_e32 v158, v174
	v_lshl_add_u64 v[106:107], v[158:159], 2, v[106:107]
	v_lshl_add_u64 v[106:107], v[106:107], 0, s[42:43]
	s_andn2_saveexec_b64 s[18:19], s[18:19]
	v_mov_b64_e32 v[106:107], s[24:25]
	v_cndmask_b32_e64 v158, v199, v200, s[14:15]
	v_mad_u64_u32 v[106:107], s[14:15], v108, s27, v[106:107]
	v_mad_i32_i24 v107, v109, s27, v107
	v_lshl_add_u64 v[106:107], v[106:107], 0, v[158:159]
	v_ashrrev_i32_e32 v109, 31, v174
	v_mov_b32_e32 v108, v174
	v_lshl_add_u64 v[106:107], v[108:109], 2, v[106:107]
	v_lshl_add_u64 v[106:107], v[106:107], 0, s[44:45]
	s_or_b64 exec, exec, s[18:19]

; __device__ __forceinline__ unsigned cvt_pk_bf16(float lo, float hi) { unsigned r; asm volatile("v_cvt_pk_bf16_f32 %0, %1, %2" : "=v"(r) : "v"(lo), "v"(hi)); return r; }
;     __device__ __forceinline__ void operator()(AccT acc, const Unit& u, int wr, int wc, int fr, int fq) const {
;     ...
;             const int sq = seq_of_row(row); const bool isS = row >= NPROMPT; const int t = isS ? ((row - NPROMPT) & 7) : (row & (SEQ - 1));
;             if (!uni) { const float* sw = SHW + (size_t)sq * NZT + col0;
; #pragma unroll
;                 for (int bj = 0; bj < 2; ++bj) { sh[bj][0] = *(const f32x4*)(sw + bj * HALF); sh[bj][1] = *(const f32x4*)(sw + bj * HALF + 4); }
;                 asm volatile("" :: "v"(sh[0][0]), "v"(sh[0][1]), "v"(sh[1][0]), "v"(sh[1][1])); }
; #pragma unroll
;             for (int bj = 0; bj < 2; ++bj) { const int c = col0 + bj * HALF;
;                 const f32x4 v0 = acc[ai][bj][m][0] * rs + sh[bj][0], v1 = acc[ai][bj][m][1] * rs + sh[bj][1];
;                 if (u.pn < 48) {
;                     u32x4 w; w.x = cvt_pk_bf16(v0[0], v0[1]); w.y = cvt_pk_bf16(v0[2], v0[3]); w.z = cvt_pk_bf16(v1[0], v1[1]); w.w = cvt_pk_bf16(v1[2], v1[3]);
;                     *(u32x4*)ZP(Z, row, c) = w;
;                     if (side) {
;                         float* dst = nullptr;
;                         if (side == 1) {
;                             const int kv = c >= ZV ? 1 : 0, cc = c - (kv ? ZV : ZK), g = cc >> 9, ci = cc & 511; const int keep = g == 0 ? 128 : (g == 1 ? 512 : 2048);
;                             if (isS) dst = out + (g == 0 ? O_SKV1 : (g == 1 ? O_SKV2 : O_SKV3)) + ((size_t)(l * 32 + (sq - 16)) * 8 + t) * 1024 + kv * 512 + ci;
;                             else if (t >= SEQ - keep) dst = out + (g == 0 ? O_PKV1 : (g == 1 ? O_PKV2 : O_PKV3)) + ((size_t)(l * 16 + sq) * keep + (t - (SEQ - keep))) * 1024 + kv * 512 + ci;
.LBB0_892:
	v_and_b32_e32 v108, 0x7ff, v106
	v_cndmask_b32_e64 v100, v108, v161, s[14:15]
	v_lshl_add_u64 v[98:99], s[54:55], 0, v[106:107]
	v_cndmask_b32_e64 v101, v196, 5, s[14:15]
	v_lshlrev_b64 v[98:99], 9, v[98:99]
	v_sub_co_u32_e32 v158, vcc, v100, v101
	s_xor_b64 s[58:59], vcc, -1
	s_andn2_b64 vcc, exec, s[16:17]
	v_lshl_add_u64 v[98:99], s[22:23], 0, v[98:99]
	s_cbranch_vccnz .LBB0_905
	v_mov_b32_e32 v147, v159
	v_lshl_add_u64 v[100:101], v[98:99], 0, v[146:147]
	s_cmp_lt_i32 s47, 1
	v_cvt_pk_bf16_f32 v110, v94, v95
	v_cvt_pk_bf16_f32 v111, v96, v97
	v_cvt_pk_bf16_f32 v112, v90, v91
	v_cvt_pk_bf16_f32 v113, v92, v93
	ds_bpermute_b32 v234, v232, v100
	ds_bpermute_b32 v235, v232, v101
	ds_bpermute_b32 v236, v232, v110
	ds_bpermute_b32 v237, v232, v111
	ds_bpermute_b32 v238, v232, v112
	ds_bpermute_b32 v239, v232, v113
	s_waitcnt lgkmcnt(0)
	global_store_dwordx4 v[234:235], v[236:239], off
	s_cbranch_scc1 .LBB0_905
	s_cmp_lg_u32 s47, 1
	s_mov_b64 s[16:17], -1
	s_cbranch_scc0 .LBB0_1226
	v_mov_b64_e32 v[100:101], 0
	s_and_saveexec_b64 s[16:17], s[58:59]
	s_cbranch_execz .LBB0_901
	v_mov_b32_e32 v100, s56
	v_cndmask_b32_e64 v100, v100, v102, s[14:15]
	v_lshl_add_u32 v100, v100, 1, v100
	v_ashrrev_i32_e32 v101, 31, v100
	v_cmp_lt_i32_e32 vcc, s26, v174
	v_lshl_add_u64 v[106:107], v[100:101], 0, v[158:159]
	s_and_saveexec_b64 s[18:19], vcc
	s_xor_b64 s[18:19], exec, s[18:19]
	s_cbranch_execz .LBB0_898
	v_lshlrev_b64 v[106:107], 12, v[106:107]
	v_cndmask_b32_e64 v100, v197, v198, s[14:15]
	v_mov_b32_e32 v101, v159
	v_lshl_add_u64 v[106:107], s[24:25], 0, v[106:107]
	v_lshl_add_u64 v[100:101], v[106:107], 0, v[100:101]
	v_mov_b32_e32 v106, v174
	v_mov_b32_e32 v107, v159
	s_movk_i32 s20, 0x9000
	v_lshl_add_u64 v[100:101], v[106:107], 2, v[100:101]
	s_mov_b32 s21, -1
	v_lshl_add_u64 v[100:101], v[100:101], 0, s[20:21]

; __device__ __forceinline__ unsigned cvt_pk_bf16(float lo, float hi) { unsigned r; asm volatile("v_cvt_pk_bf16_f32 %0, %1, %2" : "=v"(r) : "v"(lo), "v"(hi)); return r; }
;     __device__ __forceinline__ void operator()(AccT acc, const Unit& u, int wr, int wc, int fr, int fq) const {
;     ...
;             for (int bj = 0; bj < 2; ++bj) { const int c = col0 + bj * HALF;
;                 const f32x4 v0 = acc[ai][bj][m][0] * rs + sh[bj][0], v1 = acc[ai][bj][m][1] * rs + sh[bj][1];
;                 if (u.pn < 48) {
;                     u32x4 w; w.x = cvt_pk_bf16(v0[0], v0[1]); w.y = cvt_pk_bf16(v0[2], v0[3]); w.z = cvt_pk_bf16(v1[0], v1[1]); w.w = cvt_pk_bf16(v1[2], v1[3]);
;                     *(u32x4*)ZP(Z, row, c) = w;
;                     if (side) {
;                         float* dst = nullptr;
;                         if (side == 1) {
;                             const int kv = c >= ZV ? 1 : 0, cc = c - (kv ? ZV : ZK), g = cc >> 9, ci = cc & 511; const int keep = g == 0 ? 128 : (g == 1 ? 512 : 2048);
;                             if (isS) dst = out + (g == 0 ? O_SKV1 : (g == 1 ? O_SKV2 : O_SKV3)) + ((size_t)(l * 32 + (sq - 16)) * 8 + t) * 1024 + kv * 512 + ci;
;                             else if (t >= SEQ - keep) dst = out + (g == 0 ? O_PKV1 : (g == 1 ? O_PKV2 : O_PKV3)) + ((size_t)(l * 16 + sq) * keep + (t - (SEQ - keep))) * 1024 + kv * 512 + ci;
.LBB0_905:
	s_and_b64 vcc, exec, s[8:9]
	s_cbranch_vccnz .LBB0_918
	v_mov_b32_e32 v105, v104
	v_mov_b32_e32 v90, v104
	v_mov_b32_e32 v91, v104
	v_mov_b32_e32 v139, v159
	v_pk_fma_f32 v[88:89], v[88:89], v[90:91], v[16:17]
	v_pk_fma_f32 v[86:87], v[86:87], v[104:105], v[14:15]
	v_pk_fma_f32 v[84:85], v[84:85], v[90:91], v[12:13]
	v_pk_fma_f32 v[82:83], v[82:83], v[104:105], v[10:11]
	v_lshl_add_u64 v[94:95], v[98:99], 0, v[138:139]
	s_cmp_lt_i32 s47, 1
	v_cvt_pk_bf16_f32 v90, v86, v87
	v_cvt_pk_bf16_f32 v91, v88, v89
	v_cvt_pk_bf16_f32 v92, v82, v83
	v_cvt_pk_bf16_f32 v93, v84, v85
	ds_bpermute_b32 v234, v232, v94
	ds_bpermute_b32 v235, v232, v95
	ds_bpermute_b32 v236, v232, v90
	ds_bpermute_b32 v237, v232, v91
	ds_bpermute_b32 v238, v232, v92
	ds_bpermute_b32 v239, v232, v93
	s_waitcnt lgkmcnt(0)
	global_store_dwordx4 v[234:235], v[236:239], off
	s_cbranch_scc1 .LBB0_918
	s_cmp_lg_u32 s47, 1
	s_mov_b64 s[16:17], -1
	s_cbranch_scc0 .LBB0_1234
	v_mov_b64_e32 v[90:91], 0
	s_and_saveexec_b64 s[16:17], s[58:59]
	s_cbranch_execz .LBB0_914
	v_mov_b32_e32 v90, s56
	v_cndmask_b32_e64 v90, v90, v102, s[14:15]
	v_lshl_add_u32 v90, v90, 1, v90
	v_ashrrev_i32_e32 v91, 31, v90
	v_cmp_lt_i32_e32 vcc, s26, v144
	v_lshl_add_u64 v[92:93], v[90:91], 0, v[158:159]
	s_and_saveexec_b64 s[18:19], vcc
	s_xor_b64 s[18:19], exec, s[18:19]
	v_lshlrev_b64 v[90:91], 12, v[92:93]
	v_cndmask_b32_e64 v158, v197, v198, s[14:15]
	v_lshl_add_u64 v[90:91], s[24:25], 0, v[90:91]
	v_lshl_add_u64 v[90:91], v[90:91], 0, v[158:159]
	v_mov_b32_e32 v158, v174
	v_lshl_add_u64 v[90:91], v[158:159], 2, v[90:91]
	v_lshl_add_u64 v[90:91], v[90:91], 0, s[42:43]
	s_andn2_saveexec_b64 s[18:19], s[18:19]
	v_mov_b64_e32 v[90:91], s[24:25]
	v_cndmask_b32_e64 v158, v199, v200, s[14:15]
	v_mad_u64_u32 v[90:91], s[14:15], v92, s27, v[90:91]
	v_mad_i32_i24 v91, v93, s27, v91
	v_lshl_add_u64 v[90:91], v[90:91], 0, v[158:159]
	v_ashrrev_i32_e32 v93, 31, v174
	v_mov_b32_e32 v92, v174
	v_lshl_add_u64 v[90:91], v[92:93], 2, v[90:91]
	v_lshl_add_u64 v[90:91], v[90:91], 0, s[44:45]
	s_or_b64 exec, exec, s[18:19]

; __device__ __forceinline__ unsigned cvt_pk_bf16(float lo, float hi) { unsigned r; asm volatile("v_cvt_pk_bf16_f32 %0, %1, %2" : "=v"(r) : "v"(lo), "v"(hi)); return r; }
;     __device__ __forceinline__ void operator()(AccT acc, const Unit& u, int wr, int wc, int fr, int fq) const {
;     ...
;             const int sq = seq_of_row(row); const bool isS = row >= NPROMPT; const int t = isS ? ((row - NPROMPT) & 7) : (row & (SEQ - 1));
;             if (!uni) { const float* sw = SHW + (size_t)sq * NZT + col0;
; #pragma unroll
;                 for (int bj = 0; bj < 2; ++bj) { sh[bj][0] = *(const f32x4*)(sw + bj * HALF); sh[bj][1] = *(const f32x4*)(sw + bj * HALF + 4); }
;                 asm volatile("" :: "v"(sh[0][0]), "v"(sh[0][1]), "v"(sh[1][0]), "v"(sh[1][1])); }
; #pragma unroll
;             for (int bj = 0; bj < 2; ++bj) { const int c = col0 + bj * HALF;
;                 const f32x4 v0 = acc[ai][bj][m][0] * rs + sh[bj][0], v1 = acc[ai][bj][m][1] * rs + sh[bj][1];
;                 if (u.pn < 48) {
;                     u32x4 w; w.x = cvt_pk_bf16(v0[0], v0[1]); w.y = cvt_pk_bf16(v0[2], v0[3]); w.z = cvt_pk_bf16(v1[0], v1[1]); w.w = cvt_pk_bf16(v1[2], v1[3]);
;                     *(u32x4*)ZP(Z, row, c) = w;
;                     if (side) {
;                         float* dst = nullptr;
;                         if (side == 1) {
;                             const int kv = c >= ZV ? 1 : 0, cc = c - (kv ? ZV : ZK), g = cc >> 9, ci = cc & 511; const int keep = g == 0 ? 128 : (g == 1 ? 512 : 2048);
;                             if (isS) dst = out + (g == 0 ? O_SKV1 : (g == 1 ? O_SKV2 : O_SKV3)) + ((size_t)(l * 32 + (sq - 16)) * 8 + t) * 1024 + kv * 512 + ci;
;                             else if (t >= SEQ - keep) dst = out + (g == 0 ? O_PKV1 : (g == 1 ? O_PKV2 : O_PKV3)) + ((size_t)(l * 16 + sq) * keep + (t - (SEQ - keep))) * 1024 + kv * 512 + ci;
.LBB0_956:
	v_and_b32_e32 v94, 0x7cf, v86
	v_cndmask_b32_e64 v84, v94, v161, s[14:15]
	v_lshl_add_u64 v[82:83], s[54:55], 0, v[86:87]
	v_cndmask_b32_e64 v85, v196, 5, s[14:15]
	v_lshlrev_b64 v[82:83], 9, v[82:83]
	v_sub_co_u32_e32 v158, vcc, v84, v85
	s_xor_b64 s[58:59], vcc, -1
	s_andn2_b64 vcc, exec, s[16:17]
	v_lshl_add_u64 v[82:83], s[22:23], 0, v[82:83]
	s_cbranch_vccnz .LBB0_969
	v_mov_b32_e32 v147, v159
	v_lshl_add_u64 v[84:85], v[82:83], 0, v[146:147]
	s_cmp_lt_i32 s47, 1
	v_cvt_pk_bf16_f32 v96, v78, v79
	v_cvt_pk_bf16_f32 v97, v80, v81
	v_cvt_pk_bf16_f32 v98, v74, v75
	v_cvt_pk_bf16_f32 v99, v76, v77
	ds_bpermute_b32 v234, v232, v84
	ds_bpermute_b32 v235, v232, v85
	ds_bpermute_b32 v236, v232, v96
	ds_bpermute_b32 v237, v232, v97
	ds_bpermute_b32 v238, v232, v98
	ds_bpermute_b32 v239, v232, v99
	s_waitcnt lgkmcnt(0)
	global_store_dwordx4 v[234:235], v[236:239], off
	s_cbranch_scc1 .LBB0_969
	s_cmp_lg_u32 s47, 1
	s_mov_b64 s[16:17], -1
	s_cbranch_scc0 .LBB0_1242
	v_mov_b64_e32 v[84:85], 0
	s_and_saveexec_b64 s[16:17], s[58:59]
	s_cbranch_execz .LBB0_965
	v_mov_b32_e32 v84, s56
	v_cndmask_b32_e64 v84, v84, v88, s[14:15]
	v_lshl_add_u32 v84, v84, 1, v84
	v_ashrrev_i32_e32 v85, 31, v84
	v_cmp_lt_i32_e32 vcc, s26, v174
	v_lshl_add_u64 v[92:93], v[84:85], 0, v[158:159]
	s_and_saveexec_b64 s[18:19], vcc
	s_xor_b64 s[18:19], exec, s[18:19]
	s_cbranch_execz .LBB0_962
	v_lshlrev_b64 v[92:93], 12, v[92:93]
	v_cndmask_b32_e64 v84, v197, v198, s[14:15]
	v_mov_b32_e32 v85, v159
	v_lshl_add_u64 v[92:93], s[24:25], 0, v[92:93]
	v_lshl_add_u64 v[84:85], v[92:93], 0, v[84:85]
	v_mov_b32_e32 v92, v174
	v_mov_b32_e32 v93, v159
	s_movk_i32 s20, 0x9000
	v_lshl_add_u64 v[84:85], v[92:93], 2, v[84:85]
	s_mov_b32 s21, -1
	v_lshl_add_u64 v[84:85], v[84:85], 0, s[20:21]

; __device__ __forceinline__ unsigned cvt_pk_bf16(float lo, float hi) { unsigned r; asm volatile("v_cvt_pk_bf16_f32 %0, %1, %2" : "=v"(r) : "v"(lo), "v"(hi)); return r; }
;     __device__ __forceinline__ void operator()(AccT acc, const Unit& u, int wr, int wc, int fr, int fq) const {
;     ...
;             for (int bj = 0; bj < 2; ++bj) { const int c = col0 + bj * HALF;
;                 const f32x4 v0 = acc[ai][bj][m][0] * rs + sh[bj][0], v1 = acc[ai][bj][m][1] * rs + sh[bj][1];
;                 if (u.pn < 48) {
;                     u32x4 w; w.x = cvt_pk_bf16(v0[0], v0[1]); w.y = cvt_pk_bf16(v0[2], v0[3]); w.z = cvt_pk_bf16(v1[0], v1[1]); w.w = cvt_pk_bf16(v1[2], v1[3]);
;                     *(u32x4*)ZP(Z, row, c) = w;
;                     if (side) {
;                         float* dst = nullptr;
;                         if (side == 1) {
;                             const int kv = c >= ZV ? 1 : 0, cc = c - (kv ? ZV : ZK), g = cc >> 9, ci = cc & 511; const int keep = g == 0 ? 128 : (g == 1 ? 512 : 2048);
;                             if (isS) dst = out + (g == 0 ? O_SKV1 : (g == 1 ? O_SKV2 : O_SKV3)) + ((size_t)(l * 32 + (sq - 16)) * 8 + t) * 1024 + kv * 512 + ci;
;                             else if (t >= SEQ - keep) dst = out + (g == 0 ? O_PKV1 : (g == 1 ? O_PKV2 : O_PKV3)) + ((size_t)(l * 16 + sq) * keep + (t - (SEQ - keep))) * 1024 + kv * 512 + ci;
.LBB0_969:
	s_and_b64 vcc, exec, s[8:9]
	s_cbranch_vccnz .LBB0_982
	v_mov_b32_e32 v91, v90
	v_mov_b32_e32 v74, v90
	v_mov_b32_e32 v75, v90
	v_mov_b32_e32 v139, v159
	v_pk_fma_f32 v[72:73], v[72:73], v[74:75], v[16:17]
	v_pk_fma_f32 v[70:71], v[70:71], v[90:91], v[14:15]
	v_pk_fma_f32 v[68:69], v[68:69], v[74:75], v[12:13]
	v_pk_fma_f32 v[66:67], v[66:67], v[90:91], v[10:11]
	v_lshl_add_u64 v[78:79], v[82:83], 0, v[138:139]
	s_cmp_lt_i32 s47, 1
	v_cvt_pk_bf16_f32 v74, v70, v71
	v_cvt_pk_bf16_f32 v75, v72, v73
	v_cvt_pk_bf16_f32 v76, v66, v67
	v_cvt_pk_bf16_f32 v77, v68, v69
	ds_bpermute_b32 v234, v232, v78
	ds_bpermute_b32 v235, v232, v79
	ds_bpermute_b32 v236, v232, v74
	ds_bpermute_b32 v237, v232, v75
	ds_bpermute_b32 v238, v232, v76
	ds_bpermute_b32 v239, v232, v77
	s_waitcnt lgkmcnt(0)
	global_store_dwordx4 v[234:235], v[236:239], off
	s_cbranch_scc1 .LBB0_982
	s_cmp_lg_u32 s47, 1
	s_mov_b64 s[16:17], -1
	s_cbranch_scc0 .LBB0_1250
	v_mov_b64_e32 v[74:75], 0
	s_and_saveexec_b64 s[16:17], s[58:59]
	s_cbranch_execz .LBB0_978
	v_mov_b32_e32 v74, s56
	v_cndmask_b32_e64 v74, v74, v88, s[14:15]
	v_lshl_add_u32 v74, v74, 1, v74
	v_ashrrev_i32_e32 v75, 31, v74
	v_cmp_lt_i32_e32 vcc, s26, v144
	v_lshl_add_u64 v[76:77], v[74:75], 0, v[158:159]
	s_and_saveexec_b64 s[18:19], vcc
	s_xor_b64 s[18:19], exec, s[18:19]
	v_lshlrev_b64 v[74:75], 12, v[76:77]
	v_cndmask_b32_e64 v158, v197, v198, s[14:15]
	v_lshl_add_u64 v[74:75], s[24:25], 0, v[74:75]
	v_lshl_add_u64 v[74:75], v[74:75], 0, v[158:159]
	v_mov_b32_e32 v158, v174
	v_lshl_add_u64 v[74:75], v[158:159], 2, v[74:75]
	v_lshl_add_u64 v[74:75], v[74:75], 0, s[42:43]
	s_andn2_saveexec_b64 s[18:19], s[18:19]
	v_mov_b64_e32 v[74:75], s[24:25]
	v_cndmask_b32_e64 v158, v199, v200, s[14:15]
	v_mad_u64_u32 v[74:75], s[14:15], v76, s27, v[74:75]
	v_mad_i32_i24 v75, v77, s27, v75
	v_lshl_add_u64 v[74:75], v[74:75], 0, v[158:159]
	v_ashrrev_i32_e32 v77, 31, v174
	v_mov_b32_e32 v76, v174
	v_lshl_add_u64 v[74:75], v[76:77], 2, v[74:75]
	v_lshl_add_u64 v[74:75], v[74:75], 0, s[44:45]
	s_or_b64 exec, exec, s[18:19]

; __device__ __forceinline__ unsigned cvt_pk_bf16(float lo, float hi) { unsigned r; asm volatile("v_cvt_pk_bf16_f32 %0, %1, %2" : "=v"(r) : "v"(lo), "v"(hi)); return r; }
;     __device__ __forceinline__ void operator()(AccT acc, const Unit& u, int wr, int wc, int fr, int fq) const {
;     ...
;             const int sq = seq_of_row(row); const bool isS = row >= NPROMPT; const int t = isS ? ((row - NPROMPT) & 7) : (row & (SEQ - 1));
;             if (!uni) { const float* sw = SHW + (size_t)sq * NZT + col0;
; #pragma unroll
;                 for (int bj = 0; bj < 2; ++bj) { sh[bj][0] = *(const f32x4*)(sw + bj * HALF); sh[bj][1] = *(const f32x4*)(sw + bj * HALF + 4); }
;                 asm volatile("" :: "v"(sh[0][0]), "v"(sh[0][1]), "v"(sh[1][0]), "v"(sh[1][1])); }
; #pragma unroll
;             for (int bj = 0; bj < 2; ++bj) { const int c = col0 + bj * HALF;
;                 const f32x4 v0 = acc[ai][bj][m][0] * rs + sh[bj][0], v1 = acc[ai][bj][m][1] * rs + sh[bj][1];
;                 if (u.pn < 48) {
;                     u32x4 w; w.x = cvt_pk_bf16(v0[0], v0[1]); w.y = cvt_pk_bf16(v0[2], v0[3]); w.z = cvt_pk_bf16(v1[0], v1[1]); w.w = cvt_pk_bf16(v1[2], v1[3]);
;                     *(u32x4*)ZP(Z, row, c) = w;
;                     if (side) {
;                         float* dst = nullptr;
;                         if (side == 1) {
;                             const int kv = c >= ZV ? 1 : 0, cc = c - (kv ? ZV : ZK), g = cc >> 9, ci = cc & 511; const int keep = g == 0 ? 128 : (g == 1 ? 512 : 2048);
;                             if (isS) dst = out + (g == 0 ? O_SKV1 : (g == 1 ? O_SKV2 : O_SKV3)) + ((size_t)(l * 32 + (sq - 16)) * 8 + t) * 1024 + kv * 512 + ci;
;                             else if (t >= SEQ - keep) dst = out + (g == 0 ? O_PKV1 : (g == 1 ? O_PKV2 : O_PKV3)) + ((size_t)(l * 16 + sq) * keep + (t - (SEQ - keep))) * 1024 + kv * 512 + ci;
.LBB0_1020:
	v_and_b32_e32 v76, 0x7df, v74
	v_cndmask_b32_e64 v68, v76, v161, s[14:15]
	v_lshl_add_u64 v[66:67], s[54:55], 0, v[74:75]
	v_cndmask_b32_e64 v69, v196, 5, s[14:15]
	v_lshlrev_b64 v[66:67], 9, v[66:67]
	v_sub_co_u32_e32 v158, vcc, v68, v69
	s_xor_b64 s[58:59], vcc, -1
	s_andn2_b64 vcc, exec, s[16:17]
	v_lshl_add_u64 v[66:67], s[22:23], 0, v[66:67]
	s_cbranch_vccnz .LBB0_1033
	v_mov_b32_e32 v147, v159
	v_lshl_add_u64 v[68:69], v[66:67], 0, v[146:147]
	s_cmp_lt_i32 s47, 1
	v_cvt_pk_bf16_f32 v78, v62, v63
	v_cvt_pk_bf16_f32 v79, v64, v65
	v_cvt_pk_bf16_f32 v80, v58, v59
	v_cvt_pk_bf16_f32 v81, v60, v61
	ds_bpermute_b32 v234, v232, v68
	ds_bpermute_b32 v235, v232, v69
	ds_bpermute_b32 v236, v232, v78
	ds_bpermute_b32 v237, v232, v79
	ds_bpermute_b32 v238, v232, v80
	ds_bpermute_b32 v239, v232, v81
	s_waitcnt lgkmcnt(0)
	global_store_dwordx4 v[234:235], v[236:239], off
	s_cbranch_scc1 .LBB0_1033
	s_cmp_lg_u32 s47, 1
	s_mov_b64 s[16:17], -1
	s_cbranch_scc0 .LBB0_1258
	v_mov_b64_e32 v[68:69], 0
	s_and_saveexec_b64 s[16:17], s[58:59]
	s_cbranch_execz .LBB0_1029
	v_mov_b32_e32 v68, s56
	v_cndmask_b32_e64 v68, v68, v70, s[14:15]
	v_lshl_add_u32 v68, v68, 1, v68
	v_ashrrev_i32_e32 v69, 31, v68
	v_cmp_lt_i32_e32 vcc, s26, v174
	v_lshl_add_u64 v[74:75], v[68:69], 0, v[158:159]
	s_and_saveexec_b64 s[18:19], vcc
	s_xor_b64 s[18:19], exec, s[18:19]
	s_cbranch_execz .LBB0_1026
	v_lshlrev_b64 v[74:75], 12, v[74:75]
	v_cndmask_b32_e64 v68, v197, v198, s[14:15]
	v_mov_b32_e32 v69, v159
	v_lshl_add_u64 v[74:75], s[24:25], 0, v[74:75]
	v_lshl_add_u64 v[68:69], v[74:75], 0, v[68:69]
	v_mov_b32_e32 v74, v174
	v_mov_b32_e32 v75, v159
	s_movk_i32 s20, 0x9000
	v_lshl_add_u64 v[68:69], v[74:75], 2, v[68:69]
	s_mov_b32 s21, -1
	v_lshl_add_u64 v[68:69], v[68:69], 0, s[20:21]

; __device__ __forceinline__ unsigned cvt_pk_bf16(float lo, float hi) { unsigned r; asm volatile("v_cvt_pk_bf16_f32 %0, %1, %2" : "=v"(r) : "v"(lo), "v"(hi)); return r; }
;     __device__ __forceinline__ void operator()(AccT acc, const Unit& u, int wr, int wc, int fr, int fq) const {
;     ...
;             for (int bj = 0; bj < 2; ++bj) { const int c = col0 + bj * HALF;
;                 const f32x4 v0 = acc[ai][bj][m][0] * rs + sh[bj][0], v1 = acc[ai][bj][m][1] * rs + sh[bj][1];
;                 if (u.pn < 48) {
;                     u32x4 w; w.x = cvt_pk_bf16(v0[0], v0[1]); w.y = cvt_pk_bf16(v0[2], v0[3]); w.z = cvt_pk_bf16(v1[0], v1[1]); w.w = cvt_pk_bf16(v1[2], v1[3]);
;                     *(u32x4*)ZP(Z, row, c) = w;
;                     if (side) {
;                         float* dst = nullptr;
;                         if (side == 1) {
;                             const int kv = c >= ZV ? 1 : 0, cc = c - (kv ? ZV : ZK), g = cc >> 9, ci = cc & 511; const int keep = g == 0 ? 128 : (g == 1 ? 512 : 2048);
;                             if (isS) dst = out + (g == 0 ? O_SKV1 : (g == 1 ? O_SKV2 : O_SKV3)) + ((size_t)(l * 32 + (sq - 16)) * 8 + t) * 1024 + kv * 512 + ci;
;                             else if (t >= SEQ - keep) dst = out + (g == 0 ? O_PKV1 : (g == 1 ? O_PKV2 : O_PKV3)) + ((size_t)(l * 16 + sq) * keep + (t - (SEQ - keep))) * 1024 + kv * 512 + ci;
.LBB0_1033:
	s_and_b64 vcc, exec, s[8:9]
	s_cbranch_vccnz .LBB0_1046
	v_mov_b32_e32 v73, v72
	v_mov_b32_e32 v58, v72
	v_mov_b32_e32 v59, v72
	v_mov_b32_e32 v139, v159
	v_pk_fma_f32 v[56:57], v[56:57], v[58:59], v[16:17]
	v_pk_fma_f32 v[54:55], v[54:55], v[72:73], v[14:15]
	v_pk_fma_f32 v[52:53], v[52:53], v[58:59], v[12:13]
	v_pk_fma_f32 v[50:51], v[50:51], v[72:73], v[10:11]
	v_lshl_add_u64 v[62:63], v[66:67], 0, v[138:139]
	s_cmp_lt_i32 s47, 1
	v_cvt_pk_bf16_f32 v58, v54, v55
	v_cvt_pk_bf16_f32 v59, v56, v57
	v_cvt_pk_bf16_f32 v60, v50, v51
	v_cvt_pk_bf16_f32 v61, v52, v53
	ds_bpermute_b32 v234, v232, v62
	ds_bpermute_b32 v235, v232, v63
	ds_bpermute_b32 v236, v232, v58
	ds_bpermute_b32 v237, v232, v59
	ds_bpermute_b32 v238, v232, v60
	ds_bpermute_b32 v239, v232, v61
	s_waitcnt lgkmcnt(0)
	global_store_dwordx4 v[234:235], v[236:239], off
	s_cbranch_scc1 .LBB0_1046
	s_cmp_lg_u32 s47, 1
	s_mov_b64 s[16:17], -1
	s_cbranch_scc0 .LBB0_1266
	v_mov_b64_e32 v[58:59], 0
	s_and_saveexec_b64 s[16:17], s[58:59]
	s_cbranch_execz .LBB0_1042
	v_mov_b32_e32 v58, s56
	v_cndmask_b32_e64 v58, v58, v70, s[14:15]
	v_lshl_add_u32 v58, v58, 1, v58
	v_ashrrev_i32_e32 v59, 31, v58
	v_cmp_lt_i32_e32 vcc, s26, v144
	v_lshl_add_u64 v[60:61], v[58:59], 0, v[158:159]
	s_and_saveexec_b64 s[18:19], vcc
	s_xor_b64 s[18:19], exec, s[18:19]
	v_lshlrev_b64 v[58:59], 12, v[60:61]
	v_cndmask_b32_e64 v158, v197, v198, s[14:15]
	v_lshl_add_u64 v[58:59], s[24:25], 0, v[58:59]
	v_lshl_add_u64 v[58:59], v[58:59], 0, v[158:159]
	v_mov_b32_e32 v158, v174
	v_lshl_add_u64 v[58:59], v[158:159], 2, v[58:59]
	v_lshl_add_u64 v[58:59], v[58:59], 0, s[42:43]
	s_andn2_saveexec_b64 s[18:19], s[18:19]
	v_mov_b64_e32 v[58:59], s[24:25]
	v_cndmask_b32_e64 v158, v199, v200, s[14:15]
	v_mad_u64_u32 v[58:59], s[14:15], v60, s27, v[58:59]
	v_mad_i32_i24 v59, v61, s27, v59
	v_lshl_add_u64 v[58:59], v[58:59], 0, v[158:159]
	v_ashrrev_i32_e32 v61, 31, v174
	v_mov_b32_e32 v60, v174
	v_lshl_add_u64 v[58:59], v[60:61], 2, v[58:59]
	v_lshl_add_u64 v[58:59], v[58:59], 0, s[44:45]
	s_or_b64 exec, exec, s[18:19]

; __device__ __forceinline__ unsigned cvt_pk_bf16(float lo, float hi) { unsigned r; asm volatile("v_cvt_pk_bf16_f32 %0, %1, %2" : "=v"(r) : "v"(lo), "v"(hi)); return r; }
;     __device__ __forceinline__ void operator()(AccT acc, const Unit& u, int wr, int wc, int fr, int fq) const {
;     ...
;             const int sq = seq_of_row(row); const bool isS = row >= NPROMPT; const int t = isS ? ((row - NPROMPT) & 7) : (row & (SEQ - 1));
;             if (!uni) { const float* sw = SHW + (size_t)sq * NZT + col0;
; #pragma unroll
;                 for (int bj = 0; bj < 2; ++bj) { sh[bj][0] = *(const f32x4*)(sw + bj * HALF); sh[bj][1] = *(const f32x4*)(sw + bj * HALF + 4); }
;                 asm volatile("" :: "v"(sh[0][0]), "v"(sh[0][1]), "v"(sh[1][0]), "v"(sh[1][1])); }
; #pragma unroll
;             for (int bj = 0; bj < 2; ++bj) { const int c = col0 + bj * HALF;
;                 const f32x4 v0 = acc[ai][bj][m][0] * rs + sh[bj][0], v1 = acc[ai][bj][m][1] * rs + sh[bj][1];
;                 if (u.pn < 48) {
;                     u32x4 w; w.x = cvt_pk_bf16(v0[0], v0[1]); w.y = cvt_pk_bf16(v0[2], v0[3]); w.z = cvt_pk_bf16(v1[0], v1[1]); w.w = cvt_pk_bf16(v1[2], v1[3]);
;                     *(u32x4*)ZP(Z, row, c) = w;
;                     if (side) {
;                         float* dst = nullptr;
;                         if (side == 1) {
;                             const int kv = c >= ZV ? 1 : 0, cc = c - (kv ? ZV : ZK), g = cc >> 9, ci = cc & 511; const int keep = g == 0 ? 128 : (g == 1 ? 512 : 2048);
;                             if (isS) dst = out + (g == 0 ? O_SKV1 : (g == 1 ? O_SKV2 : O_SKV3)) + ((size_t)(l * 32 + (sq - 16)) * 8 + t) * 1024 + kv * 512 + ci;
;                             else if (t >= SEQ - keep) dst = out + (g == 0 ? O_PKV1 : (g == 1 ? O_PKV2 : O_PKV3)) + ((size_t)(l * 16 + sq) * keep + (t - (SEQ - keep))) * 1024 + kv * 512 + ci;
.LBB0_1084:
	v_and_b32_e32 v60, 0x7ef, v58
	v_cndmask_b32_e64 v52, v60, v161, s[14:15]
	v_lshl_add_u64 v[50:51], s[54:55], 0, v[58:59]
	v_cndmask_b32_e64 v53, v196, 5, s[14:15]
	v_lshlrev_b64 v[50:51], 9, v[50:51]
	v_sub_co_u32_e32 v158, vcc, v52, v53
	s_xor_b64 s[58:59], vcc, -1
	s_andn2_b64 vcc, exec, s[16:17]
	v_lshl_add_u64 v[50:51], s[22:23], 0, v[50:51]
	s_cbranch_vccnz .LBB0_1097
	v_mov_b32_e32 v147, v159
	v_lshl_add_u64 v[52:53], v[50:51], 0, v[146:147]
	s_cmp_lt_i32 s47, 1
	v_cvt_pk_bf16_f32 v62, v46, v47
	v_cvt_pk_bf16_f32 v63, v48, v49
	v_cvt_pk_bf16_f32 v64, v42, v43
	v_cvt_pk_bf16_f32 v65, v44, v45
	ds_bpermute_b32 v234, v232, v52
	ds_bpermute_b32 v235, v232, v53
	ds_bpermute_b32 v236, v232, v62
	ds_bpermute_b32 v237, v232, v63
	ds_bpermute_b32 v238, v232, v64
	ds_bpermute_b32 v239, v232, v65
	s_waitcnt lgkmcnt(0)
	global_store_dwordx4 v[234:235], v[236:239], off
	s_cbranch_scc1 .LBB0_1097
	s_cmp_lg_u32 s47, 1
	s_mov_b64 s[16:17], -1
	s_cbranch_scc0 .LBB0_1274
	v_mov_b64_e32 v[52:53], 0
	s_and_saveexec_b64 s[16:17], s[58:59]
	s_cbranch_execz .LBB0_1093
	v_mov_b32_e32 v52, s56
	v_cndmask_b32_e64 v52, v52, v54, s[14:15]
	v_lshl_add_u32 v52, v52, 1, v52
	v_ashrrev_i32_e32 v53, 31, v52
	v_cmp_lt_i32_e32 vcc, s26, v174
	v_lshl_add_u64 v[58:59], v[52:53], 0, v[158:159]
	s_and_saveexec_b64 s[18:19], vcc
	s_xor_b64 s[18:19], exec, s[18:19]
	s_cbranch_execz .LBB0_1090
	v_lshlrev_b64 v[58:59], 12, v[58:59]
	v_cndmask_b32_e64 v52, v197, v198, s[14:15]
	v_mov_b32_e32 v53, v159
	v_lshl_add_u64 v[58:59], s[24:25], 0, v[58:59]
	v_lshl_add_u64 v[52:53], v[58:59], 0, v[52:53]
	v_mov_b32_e32 v58, v174
	v_mov_b32_e32 v59, v159
	s_movk_i32 s20, 0x9000
	v_lshl_add_u64 v[52:53], v[58:59], 2, v[52:53]
	s_mov_b32 s21, -1
	v_lshl_add_u64 v[52:53], v[52:53], 0, s[20:21]

; __device__ __forceinline__ unsigned cvt_pk_bf16(float lo, float hi) { unsigned r; asm volatile("v_cvt_pk_bf16_f32 %0, %1, %2" : "=v"(r) : "v"(lo), "v"(hi)); return r; }
;     __device__ __forceinline__ void operator()(AccT acc, const Unit& u, int wr, int wc, int fr, int fq) const {
;     ...
;             for (int bj = 0; bj < 2; ++bj) { const int c = col0 + bj * HALF;
;                 const f32x4 v0 = acc[ai][bj][m][0] * rs + sh[bj][0], v1 = acc[ai][bj][m][1] * rs + sh[bj][1];
;                 if (u.pn < 48) {
;                     u32x4 w; w.x = cvt_pk_bf16(v0[0], v0[1]); w.y = cvt_pk_bf16(v0[2], v0[3]); w.z = cvt_pk_bf16(v1[0], v1[1]); w.w = cvt_pk_bf16(v1[2], v1[3]);
;                     *(u32x4*)ZP(Z, row, c) = w;
;                     if (side) {
;                         float* dst = nullptr;
;                         if (side == 1) {
;                             const int kv = c >= ZV ? 1 : 0, cc = c - (kv ? ZV : ZK), g = cc >> 9, ci = cc & 511; const int keep = g == 0 ? 128 : (g == 1 ? 512 : 2048);
;                             if (isS) dst = out + (g == 0 ? O_SKV1 : (g == 1 ? O_SKV2 : O_SKV3)) + ((size_t)(l * 32 + (sq - 16)) * 8 + t) * 1024 + kv * 512 + ci;
;                             else if (t >= SEQ - keep) dst = out + (g == 0 ? O_PKV1 : (g == 1 ? O_PKV2 : O_PKV3)) + ((size_t)(l * 16 + sq) * keep + (t - (SEQ - keep))) * 1024 + kv * 512 + ci;
.LBB0_1097:
	s_and_b64 vcc, exec, s[8:9]
	s_cbranch_vccnz .LBB0_1110
	v_mov_b32_e32 v57, v56
	v_mov_b32_e32 v42, v56
	v_mov_b32_e32 v43, v56
	v_mov_b32_e32 v139, v159
	v_pk_fma_f32 v[32:33], v[32:33], v[42:43], v[16:17]
	v_pk_fma_f32 v[30:31], v[30:31], v[56:57], v[14:15]
	v_pk_fma_f32 v[28:29], v[28:29], v[42:43], v[12:13]
	v_pk_fma_f32 v[26:27], v[26:27], v[56:57], v[10:11]
	v_lshl_add_u64 v[46:47], v[50:51], 0, v[138:139]
	s_cmp_lt_i32 s47, 1
	v_cvt_pk_bf16_f32 v42, v30, v31
	v_cvt_pk_bf16_f32 v43, v32, v33
	v_cvt_pk_bf16_f32 v44, v26, v27
	v_cvt_pk_bf16_f32 v45, v28, v29
	ds_bpermute_b32 v234, v232, v46
	ds_bpermute_b32 v235, v232, v47
	ds_bpermute_b32 v236, v232, v42
	ds_bpermute_b32 v237, v232, v43
	ds_bpermute_b32 v238, v232, v44
	ds_bpermute_b32 v239, v232, v45
	s_waitcnt lgkmcnt(0)
	global_store_dwordx4 v[234:235], v[236:239], off
	s_cbranch_scc1 .LBB0_1110
	s_cmp_lg_u32 s47, 1
	s_mov_b64 s[16:17], -1
	s_cbranch_scc0 .LBB0_1282
	v_mov_b64_e32 v[42:43], 0
	s_and_saveexec_b64 s[16:17], s[58:59]
	s_cbranch_execz .LBB0_1106
	v_mov_b32_e32 v42, s56
	v_cndmask_b32_e64 v42, v42, v54, s[14:15]
	v_lshl_add_u32 v42, v42, 1, v42
	v_ashrrev_i32_e32 v43, 31, v42
	v_cmp_lt_i32_e32 vcc, s26, v144
	v_lshl_add_u64 v[44:45], v[42:43], 0, v[158:159]
	s_and_saveexec_b64 s[18:19], vcc
	s_xor_b64 s[18:19], exec, s[18:19]
	v_lshlrev_b64 v[42:43], 12, v[44:45]
	v_cndmask_b32_e64 v158, v197, v198, s[14:15]
	v_lshl_add_u64 v[42:43], s[24:25], 0, v[42:43]
	v_lshl_add_u64 v[42:43], v[42:43], 0, v[158:159]
	v_mov_b32_e32 v158, v174
	v_lshl_add_u64 v[42:43], v[158:159], 2, v[42:43]
	v_lshl_add_u64 v[42:43], v[42:43], 0, s[42:43]
	s_andn2_saveexec_b64 s[18:19], s[18:19]
	v_mov_b64_e32 v[42:43], s[24:25]
	v_cndmask_b32_e64 v158, v199, v200, s[14:15]
	v_mad_u64_u32 v[42:43], s[14:15], v44, s27, v[42:43]
	v_mad_i32_i24 v43, v45, s27, v43
	v_lshl_add_u64 v[42:43], v[42:43], 0, v[158:159]
	v_ashrrev_i32_e32 v45, 31, v174
	v_mov_b32_e32 v44, v174
	v_lshl_add_u64 v[42:43], v[44:45], 2, v[42:43]
	v_lshl_add_u64 v[42:43], v[42:43], 0, s[44:45]
	s_or_b64 exec, exec, s[18:19]

; __device__ __forceinline__ unsigned cvt_pk_bf16(float lo, float hi) { unsigned r; asm volatile("v_cvt_pk_bf16_f32 %0, %1, %2" : "=v"(r) : "v"(lo), "v"(hi)); return r; }
;     __device__ __forceinline__ void operator()(AccT acc, const Unit& u, int wr, int wc, int fr, int fq) const {
;     ...
;             const int sq = seq_of_row(row); const bool isS = row >= NPROMPT; const int t = isS ? ((row - NPROMPT) & 7) : (row & (SEQ - 1));
;             if (!uni) { const float* sw = SHW + (size_t)sq * NZT + col0;
; #pragma unroll
;                 for (int bj = 0; bj < 2; ++bj) { sh[bj][0] = *(const f32x4*)(sw + bj * HALF); sh[bj][1] = *(const f32x4*)(sw + bj * HALF + 4); }
;                 asm volatile("" :: "v"(sh[0][0]), "v"(sh[0][1]), "v"(sh[1][0]), "v"(sh[1][1])); }
; #pragma unroll
;             for (int bj = 0; bj < 2; ++bj) { const int c = col0 + bj * HALF;
;                 const f32x4 v0 = acc[ai][bj][m][0] * rs + sh[bj][0], v1 = acc[ai][bj][m][1] * rs + sh[bj][1];
;                 if (u.pn < 48) {
;                     u32x4 w; w.x = cvt_pk_bf16(v0[0], v0[1]); w.y = cvt_pk_bf16(v0[2], v0[3]); w.z = cvt_pk_bf16(v1[0], v1[1]); w.w = cvt_pk_bf16(v1[2], v1[3]);
;                     *(u32x4*)ZP(Z, row, c) = w;
;                     if (side) {
;                         float* dst = nullptr;
;                         if (side == 1) {
;                             const int kv = c >= ZV ? 1 : 0, cc = c - (kv ? ZV : ZK), g = cc >> 9, ci = cc & 511; const int keep = g == 0 ? 128 : (g == 1 ? 512 : 2048);
;                             if (isS) dst = out + (g == 0 ? O_SKV1 : (g == 1 ? O_SKV2 : O_SKV3)) + ((size_t)(l * 32 + (sq - 16)) * 8 + t) * 1024 + kv * 512 + ci;
;                             else if (t >= SEQ - keep) dst = out + (g == 0 ? O_PKV1 : (g == 1 ? O_PKV2 : O_PKV3)) + ((size_t)(l * 16 + sq) * keep + (t - (SEQ - keep))) * 1024 + kv * 512 + ci;
.LBB0_1148:
	v_and_b32_e32 v36, 0x7ff, v42
	v_cndmask_b32_e64 v28, v36, v161, s[12:13]
	v_lshl_add_u64 v[26:27], s[54:55], 0, v[42:43]
	v_cndmask_b32_e64 v29, v196, 5, s[12:13]
	v_lshlrev_b64 v[26:27], 9, v[26:27]
	v_sub_co_u32_e32 v158, vcc, v28, v29
	s_xor_b64 s[18:19], vcc, -1
	s_andn2_b64 vcc, exec, s[14:15]
	v_lshl_add_u64 v[26:27], s[22:23], 0, v[26:27]
	s_cbranch_vccnz .LBB0_1161
	v_mov_b32_e32 v147, v159
	v_lshl_add_u64 v[28:29], v[26:27], 0, v[146:147]
	s_cmp_lt_i32 s47, 1
	v_cvt_pk_bf16_f32 v38, v22, v23
	v_cvt_pk_bf16_f32 v39, v24, v25
	v_cvt_pk_bf16_f32 v40, v18, v19
	v_cvt_pk_bf16_f32 v41, v20, v21
	ds_bpermute_b32 v234, v232, v28
	ds_bpermute_b32 v235, v232, v29
	ds_bpermute_b32 v236, v232, v38
	ds_bpermute_b32 v237, v232, v39
	ds_bpermute_b32 v238, v232, v40
	ds_bpermute_b32 v239, v232, v41
	s_waitcnt lgkmcnt(0)
	global_store_dwordx4 v[234:235], v[236:239], off
	s_cbranch_scc1 .LBB0_1161
	s_cmp_lg_u32 s47, 1
	s_mov_b64 s[10:11], -1
	s_cbranch_scc0 .LBB0_1290
	v_mov_b64_e32 v[28:29], 0
	s_and_saveexec_b64 s[10:11], s[18:19]
	s_cbranch_execz .LBB0_1157
	v_mov_b32_e32 v28, s56
	v_cndmask_b32_e64 v28, v28, v30, s[12:13]
	v_lshl_add_u32 v28, v28, 1, v28
	v_ashrrev_i32_e32 v29, 31, v28
	v_cmp_lt_i32_e32 vcc, s26, v174
	v_lshl_add_u64 v[34:35], v[28:29], 0, v[158:159]
	s_and_saveexec_b64 s[14:15], vcc
	s_xor_b64 s[14:15], exec, s[14:15]
	s_cbranch_execz .LBB0_1154
	v_lshlrev_b64 v[34:35], 12, v[34:35]
	v_cndmask_b32_e64 v28, v197, v198, s[12:13]
	v_mov_b32_e32 v29, v159
	v_lshl_add_u64 v[34:35], s[24:25], 0, v[34:35]
	v_lshl_add_u64 v[28:29], v[34:35], 0, v[28:29]
	v_mov_b32_e32 v175, v159
	s_movk_i32 s16, 0x9000
	v_lshl_add_u64 v[28:29], v[174:175], 2, v[28:29]
	s_mov_b32 s17, -1
	v_lshl_add_u64 v[28:29], v[28:29], 0, s[16:17]

; __device__ __forceinline__ unsigned cvt_pk_bf16(float lo, float hi) { unsigned r; asm volatile("v_cvt_pk_bf16_f32 %0, %1, %2" : "=v"(r) : "v"(lo), "v"(hi)); return r; }
;     __device__ __forceinline__ void operator()(AccT acc, const Unit& u, int wr, int wc, int fr, int fq) const {
;     ...
;             for (int bj = 0; bj < 2; ++bj) { const int c = col0 + bj * HALF;
;                 const f32x4 v0 = acc[ai][bj][m][0] * rs + sh[bj][0], v1 = acc[ai][bj][m][1] * rs + sh[bj][1];
;                 if (u.pn < 48) {
;                     u32x4 w; w.x = cvt_pk_bf16(v0[0], v0[1]); w.y = cvt_pk_bf16(v0[2], v0[3]); w.z = cvt_pk_bf16(v1[0], v1[1]); w.w = cvt_pk_bf16(v1[2], v1[3]);
;                     *(u32x4*)ZP(Z, row, c) = w;
;                     if (side) {
;                         float* dst = nullptr;
;                         if (side == 1) {
;                             const int kv = c >= ZV ? 1 : 0, cc = c - (kv ? ZV : ZK), g = cc >> 9, ci = cc & 511; const int keep = g == 0 ? 128 : (g == 1 ? 512 : 2048);
;                             if (isS) dst = out + (g == 0 ? O_SKV1 : (g == 1 ? O_SKV2 : O_SKV3)) + ((size_t)(l * 32 + (sq - 16)) * 8 + t) * 1024 + kv * 512 + ci;
;                             else if (t >= SEQ - keep) dst = out + (g == 0 ? O_PKV1 : (g == 1 ? O_PKV2 : O_PKV3)) + ((size_t)(l * 16 + sq) * keep + (t - (SEQ - keep))) * 1024 + kv * 512 + ci;
.LBB0_1161:
	s_and_b64 vcc, exec, s[8:9]
	s_cbranch_vccnz .LBB0_1174
	v_mov_b32_e32 v33, v32
	v_mov_b32_e32 v18, v32
	v_mov_b32_e32 v19, v32
	v_mov_b32_e32 v139, v159
	v_pk_fma_f32 v[8:9], v[8:9], v[18:19], v[16:17]
	v_pk_fma_f32 v[6:7], v[6:7], v[32:33], v[14:15]
	v_pk_fma_f32 v[4:5], v[4:5], v[18:19], v[12:13]
	v_pk_fma_f32 v[2:3], v[2:3], v[32:33], v[10:11]
	v_lshl_add_u64 v[14:15], v[26:27], 0, v[138:139]
	s_cmp_lt_i32 s47, 1
	v_cvt_pk_bf16_f32 v10, v6, v7
	v_cvt_pk_bf16_f32 v11, v8, v9
	v_cvt_pk_bf16_f32 v12, v2, v3
	v_cvt_pk_bf16_f32 v13, v4, v5
	ds_bpermute_b32 v234, v232, v14
	ds_bpermute_b32 v235, v232, v15
	ds_bpermute_b32 v236, v232, v10
	ds_bpermute_b32 v237, v232, v11
	ds_bpermute_b32 v238, v232, v12
	ds_bpermute_b32 v239, v232, v13
	s_waitcnt lgkmcnt(0)
	global_store_dwordx4 v[234:235], v[236:239], off
	s_cbranch_scc1 .LBB0_1174
	s_cmp_lg_u32 s47, 1
	s_mov_b64 s[8:9], -1
	s_cbranch_scc0 .LBB0_1298
	v_mov_b64_e32 v[10:11], 0
	s_and_saveexec_b64 s[8:9], s[18:19]
	s_cbranch_execz .LBB0_1170
	v_mov_b32_e32 v10, s56
	v_cndmask_b32_e64 v10, v10, v30, s[12:13]
	v_lshl_add_u32 v10, v10, 1, v10
	v_ashrrev_i32_e32 v11, 31, v10
	v_cmp_lt_i32_e32 vcc, s26, v144
	v_lshl_add_u64 v[12:13], v[10:11], 0, v[158:159]
	s_and_saveexec_b64 s[10:11], vcc
	s_xor_b64 s[10:11], exec, s[10:11]
	v_lshlrev_b64 v[10:11], 12, v[12:13]
	v_cndmask_b32_e64 v158, v197, v198, s[12:13]
	v_lshl_add_u64 v[10:11], s[24:25], 0, v[10:11]
	v_lshl_add_u64 v[10:11], v[10:11], 0, v[158:159]
	v_mov_b32_e32 v175, v159
	v_lshl_add_u64 v[10:11], v[174:175], 2, v[10:11]
	v_lshl_add_u64 v[10:11], v[10:11], 0, s[42:43]
	s_andn2_saveexec_b64 s[10:11], s[10:11]
	v_mov_b64_e32 v[10:11], s[24:25]
	v_cndmask_b32_e64 v158, v199, v200, s[12:13]
	v_mad_u64_u32 v[10:11], s[12:13], v12, s27, v[10:11]
	v_mad_i32_i24 v11, v13, s27, v11
	v_lshl_add_u64 v[10:11], v[10:11], 0, v[158:159]
	v_ashrrev_i32_e32 v175, 31, v174
	v_lshl_add_u64 v[10:11], v[174:175], 2, v[10:11]
	v_lshl_add_u64 v[10:11], v[10:11], 0, s[44:45]
	s_or_b64 exec, exec, s[10:11]

;     __device__ __forceinline__ void operator()(AccT acc, const Unit& u, int wr, int wc, int fr, int fq) const {
;         const int col0 = u.pn * BM + wc * 32 + 8 * fq;
;         const bool uni = u.pm < NPROMPT / BM;
;         f32x4 sh[2][2] = {{(f32x4){0.f, 0.f, 0.f, 0.f}, (f32x4){0.f, 0.f, 0.f, 0.f}}, {(f32x4){0.f, 0.f, 0.f, 0.f}, (f32x4){0.f, 0.f, 0.f, 0.f}}};
;         if (uni) { const float* sw = SHW + (size_t)(u.pm >> 3) * NZT + col0;
; #pragma unroll
;             for (int bj = 0; bj < 2; ++bj) { sh[bj][0] = *(const f32x4*)(sw + bj * HALF); sh[bj][1] = *(const f32x4*)(sw + bj * HALF + 4); } }
;         float rs8[8];
; #pragma unroll
;         for (int r8 = 0; r8 < 8; ++r8) rs8[r8] = row_rs(SSQ, u.pm * BM + (r8 >> 2) * HALF + wr * 64 + (r8 & 3) * 16 + fr, fq);
;         const int side = (u.pn >= 6 && u.pn < 18) ? 1 : ((u.pn >= 22 && u.pn < 32) ? 2 : 0);
;         EPI_ROWS_BEGIN
;             const float rs = rs8[ai * 4 + m];
;             const int sq = seq_of_row(row); const bool isS = row >= NPROMPT; const int t = isS ? ((row - NPROMPT) & 7) : (row & (SEQ - 1));
.LBB0_2683:
	v_mbcnt_lo_u32_b32 v232, -1, 0
	v_mbcnt_hi_u32_b32 v232, -1, v232
	v_and_b32_e32 v233, 3, v232
	v_lshrrev_b32_e32 v232, 2, v232
	v_lshl_add_u32 v232, v233, 4, v232
	v_lshlrev_b32_e32 v232, 2, v232
	s_cmpk_gt_i32 s6, 0x7f
	v_lshl_or_b32 v174, s18, 8, v184
	s_cselect_b64 s[8:9], -1, 0
	s_cmpk_lt_i32 s6, 0x80
	s_mov_b64 s[10:11], -1
	s_cbranch_scc1 .LBB0_2685
	v_ashrrev_i32_e32 v175, 31, v174
	s_mov_b64 s[10:11], 0

; __device__ __forceinline__ unsigned cvt_pk_bf16(float lo, float hi) { unsigned r; asm volatile("v_cvt_pk_bf16_f32 %0, %1, %2" : "=v"(r) : "v"(lo), "v"(hi)); return r; }
;     __device__ __forceinline__ void operator()(AccT acc, const Unit& u, int wr, int wc, int fr, int fq) const {
;     ...
;             for (int bj = 0; bj < 2; ++bj) { const int c = col0 + bj * HALF;
;                 const f32x4 v0 = acc[ai][bj][m][0] * rs + sh[bj][0], v1 = acc[ai][bj][m][1] * rs + sh[bj][1];
;                 if (u.pn < 48) {
;                     u32x4 w; w.x = cvt_pk_bf16(v0[0], v0[1]); w.y = cvt_pk_bf16(v0[2], v0[3]); w.z = cvt_pk_bf16(v1[0], v1[1]); w.w = cvt_pk_bf16(v1[2], v1[3]);
;                     *(u32x4*)ZP(Z, row, c) = w;
;                     if (side) {
;                         float* dst = nullptr;
;                         if (side == 1) {
;                             const int kv = c >= ZV ? 1 : 0, cc = c - (kv ? ZV : ZK), g = cc >> 9, ci = cc & 511; const int keep = g == 0 ? 128 : (g == 1 ? 512 : 2048);
;                             if (isS) dst = out + (g == 0 ? O_SKV1 : (g == 1 ? O_SKV2 : O_SKV3)) + ((size_t)(l * 32 + (sq - 16)) * 8 + t) * 1024 + kv * 512 + ci;
;                             else if (t >= SEQ - keep) dst = out + (g == 0 ? O_PKV1 : (g == 1 ? O_PKV2 : O_PKV3)) + ((size_t)(l * 16 + sq) * keep + (t - (SEQ - keep))) * 1024 + kv * 512 + ci;
.LBB0_2725:
	v_and_b32_e32 v225, 0x7cf, v176
	v_mad_i64_i32 v[146:147], s[14:15], s18, v193, v[176:177]
	v_cndmask_b32_e64 v148, v225, v161, s[12:13]
	v_lshlrev_b64 v[146:147], 9, v[146:147]
	v_cndmask_b32_e64 v149, v194, 5, s[12:13]
	v_sub_co_u32_e32 v158, vcc, v148, v149
	v_lshl_add_u64 v[148:149], s[22:23], 0, v[146:147]
	v_and_b32_e32 v146, 0x78, v174
	s_xor_b64 s[56:57], vcc, -1
	s_andn2_b64 vcc, exec, s[8:9]
	v_lshlrev_b32_e32 v146, 1, v146
	s_cbranch_vccnz .LBB0_2738
	v_mov_b32_e32 v147, v159
	v_lshl_add_u64 v[226:227], v[148:149], 0, v[146:147]
	s_cmp_lt_i32 s47, 1
	v_cvt_pk_bf16_f32 v180, v142, v143
	v_cvt_pk_bf16_f32 v181, v144, v145
	v_cvt_pk_bf16_f32 v182, v138, v139
	v_cvt_pk_bf16_f32 v183, v140, v141
	ds_bpermute_b32 v234, v232, v226
	ds_bpermute_b32 v235, v232, v227
	ds_bpermute_b32 v236, v232, v180
	ds_bpermute_b32 v237, v232, v181
	ds_bpermute_b32 v238, v232, v182
	ds_bpermute_b32 v239, v232, v183
	s_waitcnt lgkmcnt(0)
	global_store_dwordx4 v[234:235], v[236:239], off
	s_cbranch_scc1 .LBB0_2738
	s_cmp_lg_u32 s47, 1
	s_mov_b64 s[8:9], -1
	s_cbranch_scc0 .LBB0_3203
	v_mov_b64_e32 v[180:181], 0
	s_and_saveexec_b64 s[8:9], s[56:57]
	s_cbranch_execz .LBB0_2734
	v_mov_b32_e32 v147, s49
	v_cndmask_b32_e64 v147, v147, v224, s[12:13]
	v_cndmask_b32_e64 v177, 16, 32, s[12:13]
	v_add_u32_e32 v147, v177, v147
	v_cmp_lt_i32_e32 vcc, s96, v174
	v_mad_i64_i32 v[182:183], s[14:15], v147, 3, v[158:159]
	s_and_saveexec_b64 s[14:15], vcc
	s_xor_b64 s[14:15], exec, s[14:15]
	s_cbranch_execz .LBB0_2731
	v_lshlrev_b64 v[182:183], 12, v[182:183]
	v_cndmask_b32_e64 v180, v195, v196, s[12:13]
	v_mov_b32_e32 v181, v159
	v_lshl_add_u64 v[182:183], s[24:25], 0, v[182:183]
	v_lshl_add_u64 v[180:181], v[182:183], 0, v[180:181]
	v_mov_b32_e32 v182, v174
	v_mov_b32_e32 v183, v159
	s_movk_i32 s16, 0x9000
	v_lshl_add_u64 v[180:181], v[182:183], 2, v[180:181]
	s_mov_b32 s17, -1
	v_lshl_add_u64 v[180:181], v[180:181], 0, s[16:17]

; __device__ __forceinline__ unsigned cvt_pk_bf16(float lo, float hi) { unsigned r; asm volatile("v_cvt_pk_bf16_f32 %0, %1, %2" : "=v"(r) : "v"(lo), "v"(hi)); return r; }
;     __device__ __forceinline__ void operator()(AccT acc, const Unit& u, int wr, int wc, int fr, int fq) const {
;     ...
;             for (int bj = 0; bj < 2; ++bj) { const int c = col0 + bj * HALF;
;                 const f32x4 v0 = acc[ai][bj][m][0] * rs + sh[bj][0], v1 = acc[ai][bj][m][1] * rs + sh[bj][1];
;                 if (u.pn < 48) {
;                     u32x4 w; w.x = cvt_pk_bf16(v0[0], v0[1]); w.y = cvt_pk_bf16(v0[2], v0[3]); w.z = cvt_pk_bf16(v1[0], v1[1]); w.w = cvt_pk_bf16(v1[2], v1[3]);
;                     *(u32x4*)ZP(Z, row, c) = w;
;                     if (side) {
;                         float* dst = nullptr;
;                         if (side == 1) {
;                             const int kv = c >= ZV ? 1 : 0, cc = c - (kv ? ZV : ZK), g = cc >> 9, ci = cc & 511; const int keep = g == 0 ? 128 : (g == 1 ? 512 : 2048);
;                             if (isS) dst = out + (g == 0 ? O_SKV1 : (g == 1 ? O_SKV2 : O_SKV3)) + ((size_t)(l * 32 + (sq - 16)) * 8 + t) * 1024 + kv * 512 + ci;
;                             else if (t >= SEQ - keep) dst = out + (g == 0 ? O_PKV1 : (g == 1 ? O_PKV2 : O_PKV3)) + ((size_t)(l * 16 + sq) * keep + (t - (SEQ - keep))) * 1024 + kv * 512 + ci;
.LBB0_2738:
	v_or_b32_e32 v144, 0x80, v174
	v_cndmask_b32_e64 v138, 0, 1, s[54:55]
	v_cmp_ne_u32_e64 s[8:9], 1, v138
	v_and_b32_e32 v138, 0xf8, v144
	s_andn2_b64 vcc, exec, s[54:55]
	v_lshlrev_b32_e32 v138, 1, v138
	s_cbranch_vccnz .LBB0_2751
	v_mov_b32_e32 v179, v178
	v_mov_b32_e32 v140, v178
	v_mov_b32_e32 v141, v178
	v_mov_b32_e32 v139, v159
	v_pk_fma_f32 v[136:137], v[136:137], v[140:141], v[16:17]
	v_pk_fma_f32 v[134:135], v[134:135], v[178:179], v[14:15]
	v_pk_fma_f32 v[132:133], v[132:133], v[140:141], v[12:13]
	v_pk_fma_f32 v[130:131], v[130:131], v[178:179], v[10:11]
	v_lshl_add_u64 v[148:149], v[148:149], 0, v[138:139]
	s_cmp_lt_i32 s47, 1
	v_cvt_pk_bf16_f32 v140, v134, v135
	v_cvt_pk_bf16_f32 v141, v136, v137
	v_cvt_pk_bf16_f32 v142, v130, v131
	v_cvt_pk_bf16_f32 v143, v132, v133
	ds_bpermute_b32 v234, v232, v148
	ds_bpermute_b32 v235, v232, v149
	ds_bpermute_b32 v236, v232, v140
	ds_bpermute_b32 v237, v232, v141
	ds_bpermute_b32 v238, v232, v142
	ds_bpermute_b32 v239, v232, v143
	s_waitcnt lgkmcnt(0)
	global_store_dwordx4 v[234:235], v[236:239], off
	s_cbranch_scc1 .LBB0_2751
	s_cmp_lg_u32 s47, 1
	s_mov_b64 s[14:15], -1
	s_cbranch_scc0 .LBB0_3211
	v_mov_b64_e32 v[140:141], 0
	s_and_saveexec_b64 s[14:15], s[56:57]
	s_cbranch_execz .LBB0_2747
	v_mov_b32_e32 v139, s49
	v_cndmask_b32_e64 v139, v139, v224, s[12:13]
	v_cndmask_b32_e64 v140, 16, 32, s[12:13]
	v_add_u32_e32 v139, v140, v139
	v_cmp_lt_i32_e32 vcc, s96, v144
	v_mad_i64_i32 v[142:143], s[16:17], v139, 3, v[158:159]
	s_and_saveexec_b64 s[16:17], vcc
	s_xor_b64 s[16:17], exec, s[16:17]
	v_lshlrev_b64 v[140:141], 12, v[142:143]
	v_cndmask_b32_e64 v158, v195, v196, s[12:13]
	v_lshl_add_u64 v[140:141], s[24:25], 0, v[140:141]
	v_lshl_add_u64 v[140:141], v[140:141], 0, v[158:159]
	v_mov_b32_e32 v158, v174
	v_lshl_add_u64 v[140:141], v[158:159], 2, v[140:141]
	v_lshl_add_u64 v[140:141], v[140:141], 0, s[42:43]
	s_andn2_saveexec_b64 s[16:17], s[16:17]
	s_cbranch_execz .LBB0_2746
	v_mov_b64_e32 v[140:141], s[24:25]
	v_cndmask_b32_e64 v158, v197, v198, s[12:13]
	v_mad_u64_u32 v[140:141], s[12:13], v142, s97, v[140:141]
	v_mov_b32_e32 v142, v141
	v_mad_u64_u32 v[142:143], s[12:13], v143, s97, v[142:143]
	v_mov_b32_e32 v141, v142
	v_lshl_add_u64 v[140:141], v[140:141], 0, v[158:159]
	v_ashrrev_i32_e32 v143, 31, v174
	v_mov_b32_e32 v142, v174
	v_lshl_add_u64 v[140:141], v[142:143], 2, v[140:141]
	v_lshl_add_u64 v[140:141], v[140:141], 0, s[44:45]

; __device__ __forceinline__ unsigned cvt_pk_bf16(float lo, float hi) { unsigned r; asm volatile("v_cvt_pk_bf16_f32 %0, %1, %2" : "=v"(r) : "v"(lo), "v"(hi)); return r; }
;     __device__ __forceinline__ void operator()(AccT acc, const Unit& u, int wr, int wc, int fr, int fq) const {
;     ...
;             const int sq = seq_of_row(row); const bool isS = row >= NPROMPT; const int t = isS ? ((row - NPROMPT) & 7) : (row & (SEQ - 1));
;             if (!uni) { const float* sw = SHW + (size_t)sq * NZT + col0;
; #pragma unroll
;                 for (int bj = 0; bj < 2; ++bj) { sh[bj][0] = *(const f32x4*)(sw + bj * HALF); sh[bj][1] = *(const f32x4*)(sw + bj * HALF + 4); }
;                 asm volatile("" :: "v"(sh[0][0]), "v"(sh[0][1]), "v"(sh[1][0]), "v"(sh[1][1])); }
; #pragma unroll
;             for (int bj = 0; bj < 2; ++bj) { const int c = col0 + bj * HALF;
;                 const f32x4 v0 = acc[ai][bj][m][0] * rs + sh[bj][0], v1 = acc[ai][bj][m][1] * rs + sh[bj][1];
;                 if (u.pn < 48) {
;                     u32x4 w; w.x = cvt_pk_bf16(v0[0], v0[1]); w.y = cvt_pk_bf16(v0[2], v0[3]); w.z = cvt_pk_bf16(v1[0], v1[1]); w.w = cvt_pk_bf16(v1[2], v1[3]);
;                     *(u32x4*)ZP(Z, row, c) = w;
;                     if (side) {
;                         float* dst = nullptr;
;                         if (side == 1) {
;                             const int kv = c >= ZV ? 1 : 0, cc = c - (kv ? ZV : ZK), g = cc >> 9, ci = cc & 511; const int keep = g == 0 ? 128 : (g == 1 ? 512 : 2048);
;                             if (isS) dst = out + (g == 0 ? O_SKV1 : (g == 1 ? O_SKV2 : O_SKV3)) + ((size_t)(l * 32 + (sq - 16)) * 8 + t) * 1024 + kv * 512 + ci;
;                             else if (t >= SEQ - keep) dst = out + (g == 0 ? O_PKV1 : (g == 1 ? O_PKV2 : O_PKV3)) + ((size_t)(l * 16 + sq) * keep + (t - (SEQ - keep))) * 1024 + kv * 512 + ci;
.LBB0_2789:
	s_mul_hi_i32 s55, s18, 0x8100
	s_mul_i32 s54, s18, 0x8100
	v_and_b32_e32 v140, 0x7df, v136
	v_cndmask_b32_e64 v132, v140, v161, s[14:15]
	v_lshl_add_u64 v[130:131], s[54:55], 0, v[136:137]
	v_cndmask_b32_e64 v133, v194, 5, s[14:15]
	v_lshlrev_b64 v[130:131], 9, v[130:131]
	v_sub_co_u32_e32 v158, vcc, v132, v133
	s_xor_b64 s[56:57], vcc, -1
	s_andn2_b64 vcc, exec, s[16:17]
	v_lshl_add_u64 v[130:131], s[22:23], 0, v[130:131]
	s_cbranch_vccnz .LBB0_2802
	v_mov_b32_e32 v147, v159
	v_lshl_add_u64 v[132:133], v[130:131], 0, v[146:147]
	s_cmp_lt_i32 s47, 1
	v_cvt_pk_bf16_f32 v178, v126, v127
	v_cvt_pk_bf16_f32 v179, v128, v129
	v_cvt_pk_bf16_f32 v180, v122, v123
	v_cvt_pk_bf16_f32 v181, v124, v125
	ds_bpermute_b32 v234, v232, v132
	ds_bpermute_b32 v235, v232, v133
	ds_bpermute_b32 v236, v232, v178
	ds_bpermute_b32 v237, v232, v179
	ds_bpermute_b32 v238, v232, v180
	ds_bpermute_b32 v239, v232, v181
	s_waitcnt lgkmcnt(0)
	global_store_dwordx4 v[234:235], v[236:239], off
	s_cbranch_scc1 .LBB0_2802
	s_cmp_lg_u32 s47, 1
	s_mov_b64 s[16:17], -1
	s_cbranch_scc0 .LBB0_3219
	v_mov_b64_e32 v[132:133], 0
	s_and_saveexec_b64 s[16:17], s[56:57]
	s_cbranch_execz .LBB0_2798
	v_mov_b32_e32 v132, s49
	v_cndmask_b32_e64 v132, v132, v142, s[14:15]
	v_cndmask_b32_e64 v133, 16, 32, s[14:15]
	v_add_u32_e32 v132, v133, v132
	v_cmp_lt_i32_e32 vcc, s96, v174
	v_mad_i64_i32 v[136:137], s[18:19], v132, 3, v[158:159]
	s_and_saveexec_b64 s[18:19], vcc
	s_xor_b64 s[18:19], exec, s[18:19]
	s_cbranch_execz .LBB0_2795
	v_lshlrev_b64 v[136:137], 12, v[136:137]
	v_cndmask_b32_e64 v132, v195, v196, s[14:15]
	v_mov_b32_e32 v133, v159
	v_lshl_add_u64 v[136:137], s[24:25], 0, v[136:137]
	v_lshl_add_u64 v[132:133], v[136:137], 0, v[132:133]
	v_mov_b32_e32 v136, v174
	v_mov_b32_e32 v137, v159
	s_movk_i32 s20, 0x9000
	v_lshl_add_u64 v[132:133], v[136:137], 2, v[132:133]
	s_mov_b32 s21, -1
	v_lshl_add_u64 v[132:133], v[132:133], 0, s[20:21]

; __device__ __forceinline__ unsigned cvt_pk_bf16(float lo, float hi) { unsigned r; asm volatile("v_cvt_pk_bf16_f32 %0, %1, %2" : "=v"(r) : "v"(lo), "v"(hi)); return r; }
;     __device__ __forceinline__ void operator()(AccT acc, const Unit& u, int wr, int wc, int fr, int fq) const {
;     ...
;             for (int bj = 0; bj < 2; ++bj) { const int c = col0 + bj * HALF;
;                 const f32x4 v0 = acc[ai][bj][m][0] * rs + sh[bj][0], v1 = acc[ai][bj][m][1] * rs + sh[bj][1];
;                 if (u.pn < 48) {
;                     u32x4 w; w.x = cvt_pk_bf16(v0[0], v0[1]); w.y = cvt_pk_bf16(v0[2], v0[3]); w.z = cvt_pk_bf16(v1[0], v1[1]); w.w = cvt_pk_bf16(v1[2], v1[3]);
;                     *(u32x4*)ZP(Z, row, c) = w;
;                     if (side) {
;                         float* dst = nullptr;
;                         if (side == 1) {
;                             const int kv = c >= ZV ? 1 : 0, cc = c - (kv ? ZV : ZK), g = cc >> 9, ci = cc & 511; const int keep = g == 0 ? 128 : (g == 1 ? 512 : 2048);
;                             if (isS) dst = out + (g == 0 ? O_SKV1 : (g == 1 ? O_SKV2 : O_SKV3)) + ((size_t)(l * 32 + (sq - 16)) * 8 + t) * 1024 + kv * 512 + ci;
;                             else if (t >= SEQ - keep) dst = out + (g == 0 ? O_PKV1 : (g == 1 ? O_PKV2 : O_PKV3)) + ((size_t)(l * 16 + sq) * keep + (t - (SEQ - keep))) * 1024 + kv * 512 + ci;
.LBB0_2802:
	s_and_b64 vcc, exec, s[8:9]
	s_cbranch_vccnz .LBB0_2815
	v_mov_b32_e32 v135, v134
	v_mov_b32_e32 v122, v134
	v_mov_b32_e32 v123, v134
	v_mov_b32_e32 v139, v159
	v_pk_fma_f32 v[120:121], v[120:121], v[122:123], v[16:17]
	v_pk_fma_f32 v[118:119], v[118:119], v[134:135], v[14:15]
	v_pk_fma_f32 v[116:117], v[116:117], v[122:123], v[12:13]
	v_pk_fma_f32 v[114:115], v[114:115], v[134:135], v[10:11]
	v_lshl_add_u64 v[126:127], v[130:131], 0, v[138:139]
	s_cmp_lt_i32 s47, 1
	v_cvt_pk_bf16_f32 v122, v118, v119
	v_cvt_pk_bf16_f32 v123, v120, v121
	v_cvt_pk_bf16_f32 v124, v114, v115
	v_cvt_pk_bf16_f32 v125, v116, v117
	ds_bpermute_b32 v234, v232, v126
	ds_bpermute_b32 v235, v232, v127
	ds_bpermute_b32 v236, v232, v122
	ds_bpermute_b32 v237, v232, v123
	ds_bpermute_b32 v238, v232, v124
	ds_bpermute_b32 v239, v232, v125
	s_waitcnt lgkmcnt(0)
	global_store_dwordx4 v[234:235], v[236:239], off
	s_cbranch_scc1 .LBB0_2815
	s_cmp_lg_u32 s47, 1
	s_mov_b64 s[16:17], -1
	s_cbranch_scc0 .LBB0_3227
	v_mov_b64_e32 v[122:123], 0
	s_and_saveexec_b64 s[16:17], s[56:57]
	s_cbranch_execz .LBB0_2811
	v_mov_b32_e32 v122, s49
	v_cndmask_b32_e64 v122, v122, v142, s[14:15]
	v_cndmask_b32_e64 v123, 16, 32, s[14:15]
	v_add_u32_e32 v122, v123, v122
	v_cmp_lt_i32_e32 vcc, s96, v144
	v_mad_i64_i32 v[124:125], s[18:19], v122, 3, v[158:159]
	s_and_saveexec_b64 s[18:19], vcc
	s_xor_b64 s[18:19], exec, s[18:19]
	v_lshlrev_b64 v[122:123], 12, v[124:125]
	v_cndmask_b32_e64 v158, v195, v196, s[14:15]
	v_lshl_add_u64 v[122:123], s[24:25], 0, v[122:123]
	v_lshl_add_u64 v[122:123], v[122:123], 0, v[158:159]
	v_mov_b32_e32 v158, v174
	v_lshl_add_u64 v[122:123], v[158:159], 2, v[122:123]
	v_lshl_add_u64 v[122:123], v[122:123], 0, s[42:43]
	s_andn2_saveexec_b64 s[18:19], s[18:19]
	s_cbranch_execz .LBB0_2810
	v_mov_b64_e32 v[122:123], s[24:25]
	v_cndmask_b32_e64 v158, v197, v198, s[14:15]
	v_mad_u64_u32 v[122:123], s[14:15], v124, s97, v[122:123]
	v_mov_b32_e32 v124, v123
	v_mad_u64_u32 v[124:125], s[14:15], v125, s97, v[124:125]
	v_mov_b32_e32 v123, v124
	v_lshl_add_u64 v[122:123], v[122:123], 0, v[158:159]
	v_ashrrev_i32_e32 v125, 31, v174
	v_mov_b32_e32 v124, v174
	v_lshl_add_u64 v[122:123], v[124:125], 2, v[122:123]
	v_lshl_add_u64 v[122:123], v[122:123], 0, s[44:45]

; __device__ __forceinline__ unsigned cvt_pk_bf16(float lo, float hi) { unsigned r; asm volatile("v_cvt_pk_bf16_f32 %0, %1, %2" : "=v"(r) : "v"(lo), "v"(hi)); return r; }
;     __device__ __forceinline__ void operator()(AccT acc, const Unit& u, int wr, int wc, int fr, int fq) const {
;     ...
;             const int sq = seq_of_row(row); const bool isS = row >= NPROMPT; const int t = isS ? ((row - NPROMPT) & 7) : (row & (SEQ - 1));
;             if (!uni) { const float* sw = SHW + (size_t)sq * NZT + col0;
; #pragma unroll
;                 for (int bj = 0; bj < 2; ++bj) { sh[bj][0] = *(const f32x4*)(sw + bj * HALF); sh[bj][1] = *(const f32x4*)(sw + bj * HALF + 4); }
;                 asm volatile("" :: "v"(sh[0][0]), "v"(sh[0][1]), "v"(sh[1][0]), "v"(sh[1][1])); }
; #pragma unroll
;             for (int bj = 0; bj < 2; ++bj) { const int c = col0 + bj * HALF;
;                 const f32x4 v0 = acc[ai][bj][m][0] * rs + sh[bj][0], v1 = acc[ai][bj][m][1] * rs + sh[bj][1];
;                 if (u.pn < 48) {
;                     u32x4 w; w.x = cvt_pk_bf16(v0[0], v0[1]); w.y = cvt_pk_bf16(v0[2], v0[3]); w.z = cvt_pk_bf16(v1[0], v1[1]); w.w = cvt_pk_bf16(v1[2], v1[3]);
;                     *(u32x4*)ZP(Z, row, c) = w;
;                     if (side) {
;                         float* dst = nullptr;
;                         if (side == 1) {
;                             const int kv = c >= ZV ? 1 : 0, cc = c - (kv ? ZV : ZK), g = cc >> 9, ci = cc & 511; const int keep = g == 0 ? 128 : (g == 1 ? 512 : 2048);
;                             if (isS) dst = out + (g == 0 ? O_SKV1 : (g == 1 ? O_SKV2 : O_SKV3)) + ((size_t)(l * 32 + (sq - 16)) * 8 + t) * 1024 + kv * 512 + ci;
;                             else if (t >= SEQ - keep) dst = out + (g == 0 ? O_PKV1 : (g == 1 ? O_PKV2 : O_PKV3)) + ((size_t)(l * 16 + sq) * keep + (t - (SEQ - keep))) * 1024 + kv * 512 + ci;
.LBB0_2853:
	v_and_b32_e32 v122, 0x7ef, v120
	v_cndmask_b32_e64 v116, v122, v161, s[14:15]
	v_lshl_add_u64 v[114:115], s[54:55], 0, v[120:121]
	v_cndmask_b32_e64 v117, v194, 5, s[14:15]
	v_lshlrev_b64 v[114:115], 9, v[114:115]
	v_sub_co_u32_e32 v158, vcc, v116, v117
	s_xor_b64 s[56:57], vcc, -1
	s_andn2_b64 vcc, exec, s[16:17]
	v_lshl_add_u64 v[114:115], s[22:23], 0, v[114:115]
	s_cbranch_vccnz .LBB0_2866
	v_mov_b32_e32 v147, v159
	v_lshl_add_u64 v[116:117], v[114:115], 0, v[146:147]
	s_cmp_lt_i32 s47, 1
	v_cvt_pk_bf16_f32 v126, v110, v111
	v_cvt_pk_bf16_f32 v127, v112, v113
	v_cvt_pk_bf16_f32 v128, v106, v107
	v_cvt_pk_bf16_f32 v129, v108, v109
	ds_bpermute_b32 v234, v232, v116
	ds_bpermute_b32 v235, v232, v117
	ds_bpermute_b32 v236, v232, v126
	ds_bpermute_b32 v237, v232, v127
	ds_bpermute_b32 v238, v232, v128
	ds_bpermute_b32 v239, v232, v129
	s_waitcnt lgkmcnt(0)
	global_store_dwordx4 v[234:235], v[236:239], off
	s_cbranch_scc1 .LBB0_2866
	s_cmp_lg_u32 s47, 1
	s_mov_b64 s[16:17], -1
	s_cbranch_scc0 .LBB0_3235
	v_mov_b64_e32 v[116:117], 0
	s_and_saveexec_b64 s[16:17], s[56:57]
	s_cbranch_execz .LBB0_2862
	v_mov_b32_e32 v116, s49
	v_cndmask_b32_e64 v116, v116, v124, s[14:15]
	v_cndmask_b32_e64 v117, 16, 32, s[14:15]
	v_add_u32_e32 v116, v117, v116
	v_cmp_lt_i32_e32 vcc, s96, v174
	v_mad_i64_i32 v[120:121], s[18:19], v116, 3, v[158:159]
	s_and_saveexec_b64 s[18:19], vcc
	s_xor_b64 s[18:19], exec, s[18:19]
	s_cbranch_execz .LBB0_2859
	v_lshlrev_b64 v[120:121], 12, v[120:121]
	v_cndmask_b32_e64 v116, v195, v196, s[14:15]
	v_mov_b32_e32 v117, v159
	v_lshl_add_u64 v[120:121], s[24:25], 0, v[120:121]
	v_lshl_add_u64 v[116:117], v[120:121], 0, v[116:117]
	v_mov_b32_e32 v120, v174
	v_mov_b32_e32 v121, v159
	s_movk_i32 s20, 0x9000
	v_lshl_add_u64 v[116:117], v[120:121], 2, v[116:117]
	s_mov_b32 s21, -1
	v_lshl_add_u64 v[116:117], v[116:117], 0, s[20:21]

; __device__ __forceinline__ unsigned cvt_pk_bf16(float lo, float hi) { unsigned r; asm volatile("v_cvt_pk_bf16_f32 %0, %1, %2" : "=v"(r) : "v"(lo), "v"(hi)); return r; }
;     __device__ __forceinline__ void operator()(AccT acc, const Unit& u, int wr, int wc, int fr, int fq) const {
;     ...
;             for (int bj = 0; bj < 2; ++bj) { const int c = col0 + bj * HALF;
;                 const f32x4 v0 = acc[ai][bj][m][0] * rs + sh[bj][0], v1 = acc[ai][bj][m][1] * rs + sh[bj][1];
;                 if (u.pn < 48) {
;                     u32x4 w; w.x = cvt_pk_bf16(v0[0], v0[1]); w.y = cvt_pk_bf16(v0[2], v0[3]); w.z = cvt_pk_bf16(v1[0], v1[1]); w.w = cvt_pk_bf16(v1[2], v1[3]);
;                     *(u32x4*)ZP(Z, row, c) = w;
;                     if (side) {
;                         float* dst = nullptr;
;                         if (side == 1) {
;                             const int kv = c >= ZV ? 1 : 0, cc = c - (kv ? ZV : ZK), g = cc >> 9, ci = cc & 511; const int keep = g == 0 ? 128 : (g == 1 ? 512 : 2048);
;                             if (isS) dst = out + (g == 0 ? O_SKV1 : (g == 1 ? O_SKV2 : O_SKV3)) + ((size_t)(l * 32 + (sq - 16)) * 8 + t) * 1024 + kv * 512 + ci;
;                             else if (t >= SEQ - keep) dst = out + (g == 0 ? O_PKV1 : (g == 1 ? O_PKV2 : O_PKV3)) + ((size_t)(l * 16 + sq) * keep + (t - (SEQ - keep))) * 1024 + kv * 512 + ci;
.LBB0_2866:
	s_and_b64 vcc, exec, s[8:9]
	s_cbranch_vccnz .LBB0_2879
	v_mov_b32_e32 v119, v118
	v_mov_b32_e32 v106, v118
	v_mov_b32_e32 v107, v118
	v_mov_b32_e32 v139, v159
	v_pk_fma_f32 v[104:105], v[104:105], v[106:107], v[16:17]
	v_pk_fma_f32 v[102:103], v[102:103], v[118:119], v[14:15]
	v_pk_fma_f32 v[100:101], v[100:101], v[106:107], v[12:13]
	v_pk_fma_f32 v[98:99], v[98:99], v[118:119], v[10:11]
	v_lshl_add_u64 v[110:111], v[114:115], 0, v[138:139]
	s_cmp_lt_i32 s47, 1
	v_cvt_pk_bf16_f32 v106, v102, v103
	v_cvt_pk_bf16_f32 v107, v104, v105
	v_cvt_pk_bf16_f32 v108, v98, v99
	v_cvt_pk_bf16_f32 v109, v100, v101
	ds_bpermute_b32 v234, v232, v110
	ds_bpermute_b32 v235, v232, v111
	ds_bpermute_b32 v236, v232, v106
	ds_bpermute_b32 v237, v232, v107
	ds_bpermute_b32 v238, v232, v108
	ds_bpermute_b32 v239, v232, v109
	s_waitcnt lgkmcnt(0)
	global_store_dwordx4 v[234:235], v[236:239], off
	s_cbranch_scc1 .LBB0_2879
	s_cmp_lg_u32 s47, 1
	s_mov_b64 s[16:17], -1
	s_cbranch_scc0 .LBB0_3243
	v_mov_b64_e32 v[106:107], 0
	s_and_saveexec_b64 s[16:17], s[56:57]
	s_cbranch_execz .LBB0_2875
	v_mov_b32_e32 v106, s49
	v_cndmask_b32_e64 v106, v106, v124, s[14:15]
	v_cndmask_b32_e64 v107, 16, 32, s[14:15]
	v_add_u32_e32 v106, v107, v106
	v_cmp_lt_i32_e32 vcc, s96, v144
	v_mad_i64_i32 v[108:109], s[18:19], v106, 3, v[158:159]
	s_and_saveexec_b64 s[18:19], vcc
	s_xor_b64 s[18:19], exec, s[18:19]
	v_lshlrev_b64 v[106:107], 12, v[108:109]
	v_cndmask_b32_e64 v158, v195, v196, s[14:15]
	v_lshl_add_u64 v[106:107], s[24:25], 0, v[106:107]
	v_lshl_add_u64 v[106:107], v[106:107], 0, v[158:159]
	v_mov_b32_e32 v158, v174
	v_lshl_add_u64 v[106:107], v[158:159], 2, v[106:107]
	v_lshl_add_u64 v[106:107], v[106:107], 0, s[42:43]
	s_andn2_saveexec_b64 s[18:19], s[18:19]
	s_cbranch_execz .LBB0_2874
	v_mov_b64_e32 v[106:107], s[24:25]
	v_cndmask_b32_e64 v158, v197, v198, s[14:15]
	v_mad_u64_u32 v[106:107], s[14:15], v108, s97, v[106:107]
	v_mov_b32_e32 v108, v107
	v_mad_u64_u32 v[108:109], s[14:15], v109, s97, v[108:109]
	v_mov_b32_e32 v107, v108
	v_lshl_add_u64 v[106:107], v[106:107], 0, v[158:159]
	v_ashrrev_i32_e32 v109, 31, v174
	v_mov_b32_e32 v108, v174
	v_lshl_add_u64 v[106:107], v[108:109], 2, v[106:107]
	v_lshl_add_u64 v[106:107], v[106:107], 0, s[44:45]

; __device__ __forceinline__ unsigned cvt_pk_bf16(float lo, float hi) { unsigned r; asm volatile("v_cvt_pk_bf16_f32 %0, %1, %2" : "=v"(r) : "v"(lo), "v"(hi)); return r; }
;     __device__ __forceinline__ void operator()(AccT acc, const Unit& u, int wr, int wc, int fr, int fq) const {
;     ...
;             const int sq = seq_of_row(row); const bool isS = row >= NPROMPT; const int t = isS ? ((row - NPROMPT) & 7) : (row & (SEQ - 1));
;             if (!uni) { const float* sw = SHW + (size_t)sq * NZT + col0;
; #pragma unroll
;                 for (int bj = 0; bj < 2; ++bj) { sh[bj][0] = *(const f32x4*)(sw + bj * HALF); sh[bj][1] = *(const f32x4*)(sw + bj * HALF + 4); }
;                 asm volatile("" :: "v"(sh[0][0]), "v"(sh[0][1]), "v"(sh[1][0]), "v"(sh[1][1])); }
; #pragma unroll
;             for (int bj = 0; bj < 2; ++bj) { const int c = col0 + bj * HALF;
;                 const f32x4 v0 = acc[ai][bj][m][0] * rs + sh[bj][0], v1 = acc[ai][bj][m][1] * rs + sh[bj][1];
;                 if (u.pn < 48) {
;                     u32x4 w; w.x = cvt_pk_bf16(v0[0], v0[1]); w.y = cvt_pk_bf16(v0[2], v0[3]); w.z = cvt_pk_bf16(v1[0], v1[1]); w.w = cvt_pk_bf16(v1[2], v1[3]);
;                     *(u32x4*)ZP(Z, row, c) = w;
;                     if (side) {
;                         float* dst = nullptr;
;                         if (side == 1) {
;                             const int kv = c >= ZV ? 1 : 0, cc = c - (kv ? ZV : ZK), g = cc >> 9, ci = cc & 511; const int keep = g == 0 ? 128 : (g == 1 ? 512 : 2048);
;                             if (isS) dst = out + (g == 0 ? O_SKV1 : (g == 1 ? O_SKV2 : O_SKV3)) + ((size_t)(l * 32 + (sq - 16)) * 8 + t) * 1024 + kv * 512 + ci;
;                             else if (t >= SEQ - keep) dst = out + (g == 0 ? O_PKV1 : (g == 1 ? O_PKV2 : O_PKV3)) + ((size_t)(l * 16 + sq) * keep + (t - (SEQ - keep))) * 1024 + kv * 512 + ci;
.LBB0_2917:
	v_and_b32_e32 v106, 0x7ff, v104
	v_cndmask_b32_e64 v100, v106, v161, s[14:15]
	v_lshl_add_u64 v[98:99], s[54:55], 0, v[104:105]
	v_cndmask_b32_e64 v101, v194, 5, s[14:15]
	v_lshlrev_b64 v[98:99], 9, v[98:99]
	v_sub_co_u32_e32 v158, vcc, v100, v101
	s_xor_b64 s[56:57], vcc, -1
	s_andn2_b64 vcc, exec, s[16:17]
	v_lshl_add_u64 v[98:99], s[22:23], 0, v[98:99]
	s_cbranch_vccnz .LBB0_2930
	v_mov_b32_e32 v147, v159
	v_lshl_add_u64 v[100:101], v[98:99], 0, v[146:147]
	s_cmp_lt_i32 s47, 1
	v_cvt_pk_bf16_f32 v110, v94, v95
	v_cvt_pk_bf16_f32 v111, v96, v97
	v_cvt_pk_bf16_f32 v112, v90, v91
	v_cvt_pk_bf16_f32 v113, v92, v93
	ds_bpermute_b32 v234, v232, v100
	ds_bpermute_b32 v235, v232, v101
	ds_bpermute_b32 v236, v232, v110
	ds_bpermute_b32 v237, v232, v111
	ds_bpermute_b32 v238, v232, v112
	ds_bpermute_b32 v239, v232, v113
	s_waitcnt lgkmcnt(0)
	global_store_dwordx4 v[234:235], v[236:239], off
	s_cbranch_scc1 .LBB0_2930
	s_cmp_lg_u32 s47, 1
	s_mov_b64 s[16:17], -1
	s_cbranch_scc0 .LBB0_3251
	v_mov_b64_e32 v[100:101], 0
	s_and_saveexec_b64 s[16:17], s[56:57]
	s_cbranch_execz .LBB0_2926
	v_mov_b32_e32 v100, s49
	v_cndmask_b32_e64 v100, v100, v108, s[14:15]
	v_cndmask_b32_e64 v101, 16, 32, s[14:15]
	v_add_u32_e32 v100, v101, v100
	v_cmp_lt_i32_e32 vcc, s96, v174
	v_mad_i64_i32 v[104:105], s[18:19], v100, 3, v[158:159]
	s_and_saveexec_b64 s[18:19], vcc
	s_xor_b64 s[18:19], exec, s[18:19]
	s_cbranch_execz .LBB0_2923
	v_lshlrev_b64 v[104:105], 12, v[104:105]
	v_cndmask_b32_e64 v100, v195, v196, s[14:15]
	v_mov_b32_e32 v101, v159
	v_lshl_add_u64 v[104:105], s[24:25], 0, v[104:105]
	v_lshl_add_u64 v[100:101], v[104:105], 0, v[100:101]
	v_mov_b32_e32 v104, v174
	v_mov_b32_e32 v105, v159
	s_movk_i32 s20, 0x9000
	v_lshl_add_u64 v[100:101], v[104:105], 2, v[100:101]
	s_mov_b32 s21, -1
	v_lshl_add_u64 v[100:101], v[100:101], 0, s[20:21]

; __device__ __forceinline__ unsigned cvt_pk_bf16(float lo, float hi) { unsigned r; asm volatile("v_cvt_pk_bf16_f32 %0, %1, %2" : "=v"(r) : "v"(lo), "v"(hi)); return r; }
;     __device__ __forceinline__ void operator()(AccT acc, const Unit& u, int wr, int wc, int fr, int fq) const {
;     ...
;             for (int bj = 0; bj < 2; ++bj) { const int c = col0 + bj * HALF;
;                 const f32x4 v0 = acc[ai][bj][m][0] * rs + sh[bj][0], v1 = acc[ai][bj][m][1] * rs + sh[bj][1];
;                 if (u.pn < 48) {
;                     u32x4 w; w.x = cvt_pk_bf16(v0[0], v0[1]); w.y = cvt_pk_bf16(v0[2], v0[3]); w.z = cvt_pk_bf16(v1[0], v1[1]); w.w = cvt_pk_bf16(v1[2], v1[3]);
;                     *(u32x4*)ZP(Z, row, c) = w;
;                     if (side) {
;                         float* dst = nullptr;
;                         if (side == 1) {
;                             const int kv = c >= ZV ? 1 : 0, cc = c - (kv ? ZV : ZK), g = cc >> 9, ci = cc & 511; const int keep = g == 0 ? 128 : (g == 1 ? 512 : 2048);
;                             if (isS) dst = out + (g == 0 ? O_SKV1 : (g == 1 ? O_SKV2 : O_SKV3)) + ((size_t)(l * 32 + (sq - 16)) * 8 + t) * 1024 + kv * 512 + ci;
;                             else if (t >= SEQ - keep) dst = out + (g == 0 ? O_PKV1 : (g == 1 ? O_PKV2 : O_PKV3)) + ((size_t)(l * 16 + sq) * keep + (t - (SEQ - keep))) * 1024 + kv * 512 + ci;
.LBB0_2930:
	s_and_b64 vcc, exec, s[8:9]
	s_cbranch_vccnz .LBB0_2943
	v_mov_b32_e32 v103, v102
	v_mov_b32_e32 v90, v102
	v_mov_b32_e32 v91, v102
	v_mov_b32_e32 v139, v159
	v_pk_fma_f32 v[88:89], v[88:89], v[90:91], v[16:17]
	v_pk_fma_f32 v[86:87], v[86:87], v[102:103], v[14:15]
	v_pk_fma_f32 v[84:85], v[84:85], v[90:91], v[12:13]
	v_pk_fma_f32 v[82:83], v[82:83], v[102:103], v[10:11]
	v_lshl_add_u64 v[94:95], v[98:99], 0, v[138:139]
	s_cmp_lt_i32 s47, 1
	v_cvt_pk_bf16_f32 v90, v86, v87
	v_cvt_pk_bf16_f32 v91, v88, v89
	v_cvt_pk_bf16_f32 v92, v82, v83
	v_cvt_pk_bf16_f32 v93, v84, v85
	ds_bpermute_b32 v234, v232, v94
	ds_bpermute_b32 v235, v232, v95
	ds_bpermute_b32 v236, v232, v90
	ds_bpermute_b32 v237, v232, v91
	ds_bpermute_b32 v238, v232, v92
	ds_bpermute_b32 v239, v232, v93
	s_waitcnt lgkmcnt(0)
	global_store_dwordx4 v[234:235], v[236:239], off
	s_cbranch_scc1 .LBB0_2943
	s_cmp_lg_u32 s47, 1
	s_mov_b64 s[16:17], -1
	s_cbranch_scc0 .LBB0_3259
	v_mov_b64_e32 v[90:91], 0
	s_and_saveexec_b64 s[16:17], s[56:57]
	s_cbranch_execz .LBB0_2939
	v_mov_b32_e32 v90, s49
	v_cndmask_b32_e64 v90, v90, v108, s[14:15]
	v_cndmask_b32_e64 v91, 16, 32, s[14:15]
	v_add_u32_e32 v90, v91, v90
	v_cmp_lt_i32_e32 vcc, s96, v144
	v_mad_i64_i32 v[92:93], s[18:19], v90, 3, v[158:159]
	s_and_saveexec_b64 s[18:19], vcc
	s_xor_b64 s[18:19], exec, s[18:19]
	v_lshlrev_b64 v[90:91], 12, v[92:93]
	v_cndmask_b32_e64 v158, v195, v196, s[14:15]
	v_lshl_add_u64 v[90:91], s[24:25], 0, v[90:91]
	v_lshl_add_u64 v[90:91], v[90:91], 0, v[158:159]
	v_mov_b32_e32 v158, v174
	v_lshl_add_u64 v[90:91], v[158:159], 2, v[90:91]
	v_lshl_add_u64 v[90:91], v[90:91], 0, s[42:43]
	s_andn2_saveexec_b64 s[18:19], s[18:19]
	s_cbranch_execz .LBB0_2938
	v_mov_b64_e32 v[90:91], s[24:25]
	v_cndmask_b32_e64 v158, v197, v198, s[14:15]
	v_mad_u64_u32 v[90:91], s[14:15], v92, s97, v[90:91]
	v_mov_b32_e32 v92, v91
	v_mad_u64_u32 v[92:93], s[14:15], v93, s97, v[92:93]
	v_mov_b32_e32 v91, v92
	v_lshl_add_u64 v[90:91], v[90:91], 0, v[158:159]
	v_ashrrev_i32_e32 v93, 31, v174
	v_mov_b32_e32 v92, v174
	v_lshl_add_u64 v[90:91], v[92:93], 2, v[90:91]
	v_lshl_add_u64 v[90:91], v[90:91], 0, s[44:45]

; __device__ __forceinline__ unsigned cvt_pk_bf16(float lo, float hi) { unsigned r; asm volatile("v_cvt_pk_bf16_f32 %0, %1, %2" : "=v"(r) : "v"(lo), "v"(hi)); return r; }
;     __device__ __forceinline__ void operator()(AccT acc, const Unit& u, int wr, int wc, int fr, int fq) const {
;     ...
;             const int sq = seq_of_row(row); const bool isS = row >= NPROMPT; const int t = isS ? ((row - NPROMPT) & 7) : (row & (SEQ - 1));
;             if (!uni) { const float* sw = SHW + (size_t)sq * NZT + col0;
; #pragma unroll
;                 for (int bj = 0; bj < 2; ++bj) { sh[bj][0] = *(const f32x4*)(sw + bj * HALF); sh[bj][1] = *(const f32x4*)(sw + bj * HALF + 4); }
;                 asm volatile("" :: "v"(sh[0][0]), "v"(sh[0][1]), "v"(sh[1][0]), "v"(sh[1][1])); }
; #pragma unroll
;             for (int bj = 0; bj < 2; ++bj) { const int c = col0 + bj * HALF;
;                 const f32x4 v0 = acc[ai][bj][m][0] * rs + sh[bj][0], v1 = acc[ai][bj][m][1] * rs + sh[bj][1];
;                 if (u.pn < 48) {
;                     u32x4 w; w.x = cvt_pk_bf16(v0[0], v0[1]); w.y = cvt_pk_bf16(v0[2], v0[3]); w.z = cvt_pk_bf16(v1[0], v1[1]); w.w = cvt_pk_bf16(v1[2], v1[3]);
;                     *(u32x4*)ZP(Z, row, c) = w;
;                     if (side) {
;                         float* dst = nullptr;
;                         if (side == 1) {
;                             const int kv = c >= ZV ? 1 : 0, cc = c - (kv ? ZV : ZK), g = cc >> 9, ci = cc & 511; const int keep = g == 0 ? 128 : (g == 1 ? 512 : 2048);
;                             if (isS) dst = out + (g == 0 ? O_SKV1 : (g == 1 ? O_SKV2 : O_SKV3)) + ((size_t)(l * 32 + (sq - 16)) * 8 + t) * 1024 + kv * 512 + ci;
;                             else if (t >= SEQ - keep) dst = out + (g == 0 ? O_PKV1 : (g == 1 ? O_PKV2 : O_PKV3)) + ((size_t)(l * 16 + sq) * keep + (t - (SEQ - keep))) * 1024 + kv * 512 + ci;
.LBB0_2981:
	v_and_b32_e32 v93, 0x7cf, v86
	v_cndmask_b32_e64 v84, v93, v161, s[14:15]
	v_lshl_add_u64 v[82:83], s[54:55], 0, v[86:87]
	v_cndmask_b32_e64 v85, v194, 5, s[14:15]
	v_lshlrev_b64 v[82:83], 9, v[82:83]
	v_sub_co_u32_e32 v158, vcc, v84, v85
	s_xor_b64 s[56:57], vcc, -1
	s_andn2_b64 vcc, exec, s[16:17]
	v_lshl_add_u64 v[82:83], s[22:23], 0, v[82:83]
	s_cbranch_vccnz .LBB0_2994
	v_mov_b32_e32 v147, v159
	v_lshl_add_u64 v[84:85], v[82:83], 0, v[146:147]
	s_cmp_lt_i32 s47, 1
	v_cvt_pk_bf16_f32 v94, v78, v79
	v_cvt_pk_bf16_f32 v95, v80, v81
	v_cvt_pk_bf16_f32 v96, v74, v75
	v_cvt_pk_bf16_f32 v97, v76, v77
	ds_bpermute_b32 v234, v232, v84
	ds_bpermute_b32 v235, v232, v85
	ds_bpermute_b32 v236, v232, v94
	ds_bpermute_b32 v237, v232, v95
	ds_bpermute_b32 v238, v232, v96
	ds_bpermute_b32 v239, v232, v97
	s_waitcnt lgkmcnt(0)
	global_store_dwordx4 v[234:235], v[236:239], off
	s_cbranch_scc1 .LBB0_2994
	s_cmp_lg_u32 s47, 1
	s_mov_b64 s[16:17], -1
	s_cbranch_scc0 .LBB0_3267
	v_mov_b64_e32 v[84:85], 0
	s_and_saveexec_b64 s[16:17], s[56:57]
	s_cbranch_execz .LBB0_2990
	v_mov_b32_e32 v84, s33
	v_cndmask_b32_e64 v84, v84, v92, s[14:15]
	v_cndmask_b32_e64 v85, 16, 32, s[14:15]
	v_add_u32_e32 v84, v85, v84
	v_cmp_lt_i32_e32 vcc, s96, v174
	v_mad_i64_i32 v[90:91], s[18:19], v84, 3, v[158:159]
	s_and_saveexec_b64 s[18:19], vcc
	s_xor_b64 s[18:19], exec, s[18:19]
	s_cbranch_execz .LBB0_2987
	v_lshlrev_b64 v[90:91], 12, v[90:91]
	v_cndmask_b32_e64 v84, v195, v196, s[14:15]
	v_mov_b32_e32 v85, v159
	v_lshl_add_u64 v[90:91], s[24:25], 0, v[90:91]
	v_lshl_add_u64 v[84:85], v[90:91], 0, v[84:85]
	v_mov_b32_e32 v90, v174
	v_mov_b32_e32 v91, v159
	s_movk_i32 s20, 0x9000
	v_lshl_add_u64 v[84:85], v[90:91], 2, v[84:85]
	s_mov_b32 s21, -1
	v_lshl_add_u64 v[84:85], v[84:85], 0, s[20:21]

; __device__ __forceinline__ unsigned cvt_pk_bf16(float lo, float hi) { unsigned r; asm volatile("v_cvt_pk_bf16_f32 %0, %1, %2" : "=v"(r) : "v"(lo), "v"(hi)); return r; }
;     __device__ __forceinline__ void operator()(AccT acc, const Unit& u, int wr, int wc, int fr, int fq) const {
;     ...
;             for (int bj = 0; bj < 2; ++bj) { const int c = col0 + bj * HALF;
;                 const f32x4 v0 = acc[ai][bj][m][0] * rs + sh[bj][0], v1 = acc[ai][bj][m][1] * rs + sh[bj][1];
;                 if (u.pn < 48) {
;                     u32x4 w; w.x = cvt_pk_bf16(v0[0], v0[1]); w.y = cvt_pk_bf16(v0[2], v0[3]); w.z = cvt_pk_bf16(v1[0], v1[1]); w.w = cvt_pk_bf16(v1[2], v1[3]);
;                     *(u32x4*)ZP(Z, row, c) = w;
;                     if (side) {
;                         float* dst = nullptr;
;                         if (side == 1) {
;                             const int kv = c >= ZV ? 1 : 0, cc = c - (kv ? ZV : ZK), g = cc >> 9, ci = cc & 511; const int keep = g == 0 ? 128 : (g == 1 ? 512 : 2048);
;                             if (isS) dst = out + (g == 0 ? O_SKV1 : (g == 1 ? O_SKV2 : O_SKV3)) + ((size_t)(l * 32 + (sq - 16)) * 8 + t) * 1024 + kv * 512 + ci;
;                             else if (t >= SEQ - keep) dst = out + (g == 0 ? O_PKV1 : (g == 1 ? O_PKV2 : O_PKV3)) + ((size_t)(l * 16 + sq) * keep + (t - (SEQ - keep))) * 1024 + kv * 512 + ci;
.LBB0_2994:
	s_and_b64 vcc, exec, s[8:9]
	s_cbranch_vccnz .LBB0_3007
	v_mov_b32_e32 v89, v88
	v_mov_b32_e32 v74, v88
	v_mov_b32_e32 v75, v88
	v_mov_b32_e32 v139, v159
	v_pk_fma_f32 v[72:73], v[72:73], v[74:75], v[16:17]
	v_pk_fma_f32 v[70:71], v[70:71], v[88:89], v[14:15]
	v_pk_fma_f32 v[68:69], v[68:69], v[74:75], v[12:13]
	v_pk_fma_f32 v[66:67], v[66:67], v[88:89], v[10:11]
	v_lshl_add_u64 v[78:79], v[82:83], 0, v[138:139]
	s_cmp_lt_i32 s47, 1
	v_cvt_pk_bf16_f32 v74, v70, v71
	v_cvt_pk_bf16_f32 v75, v72, v73
	v_cvt_pk_bf16_f32 v76, v66, v67
	v_cvt_pk_bf16_f32 v77, v68, v69
	ds_bpermute_b32 v234, v232, v78
	ds_bpermute_b32 v235, v232, v79
	ds_bpermute_b32 v236, v232, v74
	ds_bpermute_b32 v237, v232, v75
	ds_bpermute_b32 v238, v232, v76
	ds_bpermute_b32 v239, v232, v77
	s_waitcnt lgkmcnt(0)
	global_store_dwordx4 v[234:235], v[236:239], off
	s_cbranch_scc1 .LBB0_3007
	s_cmp_lg_u32 s47, 1
	s_mov_b64 s[16:17], -1
	s_cbranch_scc0 .LBB0_3275
	v_mov_b64_e32 v[74:75], 0
	s_and_saveexec_b64 s[16:17], s[56:57]
	s_cbranch_execz .LBB0_3003
	v_mov_b32_e32 v74, s33
	v_cndmask_b32_e64 v74, v74, v92, s[14:15]
	v_cndmask_b32_e64 v75, 16, 32, s[14:15]
	v_add_u32_e32 v74, v75, v74
	v_cmp_lt_i32_e32 vcc, s96, v144
	v_mad_i64_i32 v[76:77], s[18:19], v74, 3, v[158:159]
	s_and_saveexec_b64 s[18:19], vcc
	s_xor_b64 s[18:19], exec, s[18:19]
	v_lshlrev_b64 v[74:75], 12, v[76:77]
	v_cndmask_b32_e64 v158, v195, v196, s[14:15]
	v_lshl_add_u64 v[74:75], s[24:25], 0, v[74:75]
	v_lshl_add_u64 v[74:75], v[74:75], 0, v[158:159]
	v_mov_b32_e32 v158, v174
	v_lshl_add_u64 v[74:75], v[158:159], 2, v[74:75]
	v_lshl_add_u64 v[74:75], v[74:75], 0, s[42:43]
	s_andn2_saveexec_b64 s[18:19], s[18:19]
	s_cbranch_execz .LBB0_3002
	v_mov_b64_e32 v[74:75], s[24:25]
	v_cndmask_b32_e64 v158, v197, v198, s[14:15]
	v_mad_u64_u32 v[74:75], s[14:15], v76, s97, v[74:75]
	v_mov_b32_e32 v76, v75
	v_mad_u64_u32 v[76:77], s[14:15], v77, s97, v[76:77]
	v_mov_b32_e32 v75, v76
	v_lshl_add_u64 v[74:75], v[74:75], 0, v[158:159]
	v_ashrrev_i32_e32 v77, 31, v174
	v_mov_b32_e32 v76, v174
	v_lshl_add_u64 v[74:75], v[76:77], 2, v[74:75]
	v_lshl_add_u64 v[74:75], v[74:75], 0, s[44:45]

; __device__ __forceinline__ unsigned cvt_pk_bf16(float lo, float hi) { unsigned r; asm volatile("v_cvt_pk_bf16_f32 %0, %1, %2" : "=v"(r) : "v"(lo), "v"(hi)); return r; }
;     __device__ __forceinline__ void operator()(AccT acc, const Unit& u, int wr, int wc, int fr, int fq) const {
;     ...
;             const int sq = seq_of_row(row); const bool isS = row >= NPROMPT; const int t = isS ? ((row - NPROMPT) & 7) : (row & (SEQ - 1));
;             if (!uni) { const float* sw = SHW + (size_t)sq * NZT + col0;
; #pragma unroll
;                 for (int bj = 0; bj < 2; ++bj) { sh[bj][0] = *(const f32x4*)(sw + bj * HALF); sh[bj][1] = *(const f32x4*)(sw + bj * HALF + 4); }
;                 asm volatile("" :: "v"(sh[0][0]), "v"(sh[0][1]), "v"(sh[1][0]), "v"(sh[1][1])); }
; #pragma unroll
;             for (int bj = 0; bj < 2; ++bj) { const int c = col0 + bj * HALF;
;                 const f32x4 v0 = acc[ai][bj][m][0] * rs + sh[bj][0], v1 = acc[ai][bj][m][1] * rs + sh[bj][1];
;                 if (u.pn < 48) {
;                     u32x4 w; w.x = cvt_pk_bf16(v0[0], v0[1]); w.y = cvt_pk_bf16(v0[2], v0[3]); w.z = cvt_pk_bf16(v1[0], v1[1]); w.w = cvt_pk_bf16(v1[2], v1[3]);
;                     *(u32x4*)ZP(Z, row, c) = w;
;                     if (side) {
;                         float* dst = nullptr;
;                         if (side == 1) {
;                             const int kv = c >= ZV ? 1 : 0, cc = c - (kv ? ZV : ZK), g = cc >> 9, ci = cc & 511; const int keep = g == 0 ? 128 : (g == 1 ? 512 : 2048);
;                             if (isS) dst = out + (g == 0 ? O_SKV1 : (g == 1 ? O_SKV2 : O_SKV3)) + ((size_t)(l * 32 + (sq - 16)) * 8 + t) * 1024 + kv * 512 + ci;
;                             else if (t >= SEQ - keep) dst = out + (g == 0 ? O_PKV1 : (g == 1 ? O_PKV2 : O_PKV3)) + ((size_t)(l * 16 + sq) * keep + (t - (SEQ - keep))) * 1024 + kv * 512 + ci;
.LBB0_3045:
	v_and_b32_e32 v74, 0x7df, v72
	v_cndmask_b32_e64 v68, v74, v161, s[14:15]
	v_lshl_add_u64 v[66:67], s[54:55], 0, v[72:73]
	v_cndmask_b32_e64 v69, v194, 5, s[14:15]
	v_lshlrev_b64 v[66:67], 9, v[66:67]
	v_sub_co_u32_e32 v158, vcc, v68, v69
	s_xor_b64 s[56:57], vcc, -1
	s_andn2_b64 vcc, exec, s[16:17]
	v_lshl_add_u64 v[66:67], s[22:23], 0, v[66:67]
	s_cbranch_vccnz .LBB0_3058
	v_mov_b32_e32 v147, v159
	v_lshl_add_u64 v[68:69], v[66:67], 0, v[146:147]
	s_cmp_lt_i32 s47, 1
	v_cvt_pk_bf16_f32 v78, v62, v63
	v_cvt_pk_bf16_f32 v79, v64, v65
	v_cvt_pk_bf16_f32 v80, v58, v59
	v_cvt_pk_bf16_f32 v81, v60, v61
	ds_bpermute_b32 v234, v232, v68
	ds_bpermute_b32 v235, v232, v69
	ds_bpermute_b32 v236, v232, v78
	ds_bpermute_b32 v237, v232, v79
	ds_bpermute_b32 v238, v232, v80
	ds_bpermute_b32 v239, v232, v81
	s_waitcnt lgkmcnt(0)
	global_store_dwordx4 v[234:235], v[236:239], off
	s_cbranch_scc1 .LBB0_3058
	s_cmp_lg_u32 s47, 1
	s_mov_b64 s[16:17], -1
	s_cbranch_scc0 .LBB0_3283
	v_mov_b64_e32 v[68:69], 0
	s_and_saveexec_b64 s[16:17], s[56:57]
	s_cbranch_execz .LBB0_3054
	v_mov_b32_e32 v68, s33
	v_cndmask_b32_e64 v68, v68, v76, s[14:15]
	v_cndmask_b32_e64 v69, 16, 32, s[14:15]
	v_add_u32_e32 v68, v69, v68
	v_cmp_lt_i32_e32 vcc, s96, v174
	v_mad_i64_i32 v[72:73], s[18:19], v68, 3, v[158:159]
	s_and_saveexec_b64 s[18:19], vcc
	s_xor_b64 s[18:19], exec, s[18:19]
	s_cbranch_execz .LBB0_3051
	v_lshlrev_b64 v[72:73], 12, v[72:73]
	v_cndmask_b32_e64 v68, v195, v196, s[14:15]
	v_mov_b32_e32 v69, v159
	v_lshl_add_u64 v[72:73], s[24:25], 0, v[72:73]
	v_lshl_add_u64 v[68:69], v[72:73], 0, v[68:69]
	v_mov_b32_e32 v72, v174
	v_mov_b32_e32 v73, v159
	s_movk_i32 s20, 0x9000
	v_lshl_add_u64 v[68:69], v[72:73], 2, v[68:69]
	s_mov_b32 s21, -1
	v_lshl_add_u64 v[68:69], v[68:69], 0, s[20:21]

; __device__ __forceinline__ unsigned cvt_pk_bf16(float lo, float hi) { unsigned r; asm volatile("v_cvt_pk_bf16_f32 %0, %1, %2" : "=v"(r) : "v"(lo), "v"(hi)); return r; }
;     __device__ __forceinline__ void operator()(AccT acc, const Unit& u, int wr, int wc, int fr, int fq) const {
;     ...
;             for (int bj = 0; bj < 2; ++bj) { const int c = col0 + bj * HALF;
;                 const f32x4 v0 = acc[ai][bj][m][0] * rs + sh[bj][0], v1 = acc[ai][bj][m][1] * rs + sh[bj][1];
;                 if (u.pn < 48) {
;                     u32x4 w; w.x = cvt_pk_bf16(v0[0], v0[1]); w.y = cvt_pk_bf16(v0[2], v0[3]); w.z = cvt_pk_bf16(v1[0], v1[1]); w.w = cvt_pk_bf16(v1[2], v1[3]);
;                     *(u32x4*)ZP(Z, row, c) = w;
;                     if (side) {
;                         float* dst = nullptr;
;                         if (side == 1) {
;                             const int kv = c >= ZV ? 1 : 0, cc = c - (kv ? ZV : ZK), g = cc >> 9, ci = cc & 511; const int keep = g == 0 ? 128 : (g == 1 ? 512 : 2048);
;                             if (isS) dst = out + (g == 0 ? O_SKV1 : (g == 1 ? O_SKV2 : O_SKV3)) + ((size_t)(l * 32 + (sq - 16)) * 8 + t) * 1024 + kv * 512 + ci;
;                             else if (t >= SEQ - keep) dst = out + (g == 0 ? O_PKV1 : (g == 1 ? O_PKV2 : O_PKV3)) + ((size_t)(l * 16 + sq) * keep + (t - (SEQ - keep))) * 1024 + kv * 512 + ci;
.LBB0_3058:
	s_and_b64 vcc, exec, s[8:9]
	s_cbranch_vccnz .LBB0_3071
	v_mov_b32_e32 v71, v70
	v_mov_b32_e32 v58, v70
	v_mov_b32_e32 v59, v70
	v_mov_b32_e32 v139, v159
	v_pk_fma_f32 v[56:57], v[56:57], v[58:59], v[16:17]
	v_pk_fma_f32 v[54:55], v[54:55], v[70:71], v[14:15]
	v_pk_fma_f32 v[52:53], v[52:53], v[58:59], v[12:13]
	v_pk_fma_f32 v[50:51], v[50:51], v[70:71], v[10:11]
	v_lshl_add_u64 v[62:63], v[66:67], 0, v[138:139]
	s_cmp_lt_i32 s47, 1
	v_cvt_pk_bf16_f32 v58, v54, v55
	v_cvt_pk_bf16_f32 v59, v56, v57
	v_cvt_pk_bf16_f32 v60, v50, v51
	v_cvt_pk_bf16_f32 v61, v52, v53
	ds_bpermute_b32 v234, v232, v62
	ds_bpermute_b32 v235, v232, v63
	ds_bpermute_b32 v236, v232, v58
	ds_bpermute_b32 v237, v232, v59
	ds_bpermute_b32 v238, v232, v60
	ds_bpermute_b32 v239, v232, v61
	s_waitcnt lgkmcnt(0)
	global_store_dwordx4 v[234:235], v[236:239], off
	s_cbranch_scc1 .LBB0_3071
	s_cmp_lg_u32 s47, 1
	s_mov_b64 s[16:17], -1
	s_cbranch_scc0 .LBB0_3291
	v_mov_b64_e32 v[58:59], 0
	s_and_saveexec_b64 s[16:17], s[56:57]
	s_cbranch_execz .LBB0_3067
	v_mov_b32_e32 v58, s33
	v_cndmask_b32_e64 v58, v58, v76, s[14:15]
	v_cndmask_b32_e64 v59, 16, 32, s[14:15]
	v_add_u32_e32 v58, v59, v58
	v_cmp_lt_i32_e32 vcc, s96, v144
	v_mad_i64_i32 v[60:61], s[18:19], v58, 3, v[158:159]
	s_and_saveexec_b64 s[18:19], vcc
	s_xor_b64 s[18:19], exec, s[18:19]
	v_lshlrev_b64 v[58:59], 12, v[60:61]
	v_cndmask_b32_e64 v158, v195, v196, s[14:15]
	v_lshl_add_u64 v[58:59], s[24:25], 0, v[58:59]
	v_lshl_add_u64 v[58:59], v[58:59], 0, v[158:159]
	v_mov_b32_e32 v158, v174
	v_lshl_add_u64 v[58:59], v[158:159], 2, v[58:59]
	v_lshl_add_u64 v[58:59], v[58:59], 0, s[42:43]
	s_andn2_saveexec_b64 s[18:19], s[18:19]
	s_cbranch_execz .LBB0_3066
	v_mov_b64_e32 v[58:59], s[24:25]
	v_cndmask_b32_e64 v158, v197, v198, s[14:15]
	v_mad_u64_u32 v[58:59], s[14:15], v60, s97, v[58:59]
	v_mov_b32_e32 v60, v59
	v_mad_u64_u32 v[60:61], s[14:15], v61, s97, v[60:61]
	v_mov_b32_e32 v59, v60
	v_lshl_add_u64 v[58:59], v[58:59], 0, v[158:159]
	v_ashrrev_i32_e32 v61, 31, v174
	v_mov_b32_e32 v60, v174
	v_lshl_add_u64 v[58:59], v[60:61], 2, v[58:59]
	v_lshl_add_u64 v[58:59], v[58:59], 0, s[44:45]

; __device__ __forceinline__ unsigned cvt_pk_bf16(float lo, float hi) { unsigned r; asm volatile("v_cvt_pk_bf16_f32 %0, %1, %2" : "=v"(r) : "v"(lo), "v"(hi)); return r; }
;     __device__ __forceinline__ void operator()(AccT acc, const Unit& u, int wr, int wc, int fr, int fq) const {
;     ...
;             const int sq = seq_of_row(row); const bool isS = row >= NPROMPT; const int t = isS ? ((row - NPROMPT) & 7) : (row & (SEQ - 1));
;             if (!uni) { const float* sw = SHW + (size_t)sq * NZT + col0;
; #pragma unroll
;                 for (int bj = 0; bj < 2; ++bj) { sh[bj][0] = *(const f32x4*)(sw + bj * HALF); sh[bj][1] = *(const f32x4*)(sw + bj * HALF + 4); }
;                 asm volatile("" :: "v"(sh[0][0]), "v"(sh[0][1]), "v"(sh[1][0]), "v"(sh[1][1])); }
; #pragma unroll
;             for (int bj = 0; bj < 2; ++bj) { const int c = col0 + bj * HALF;
;                 const f32x4 v0 = acc[ai][bj][m][0] * rs + sh[bj][0], v1 = acc[ai][bj][m][1] * rs + sh[bj][1];
;                 if (u.pn < 48) {
;                     u32x4 w; w.x = cvt_pk_bf16(v0[0], v0[1]); w.y = cvt_pk_bf16(v0[2], v0[3]); w.z = cvt_pk_bf16(v1[0], v1[1]); w.w = cvt_pk_bf16(v1[2], v1[3]);
;                     *(u32x4*)ZP(Z, row, c) = w;
;                     if (side) {
;                         float* dst = nullptr;
;                         if (side == 1) {
;                             const int kv = c >= ZV ? 1 : 0, cc = c - (kv ? ZV : ZK), g = cc >> 9, ci = cc & 511; const int keep = g == 0 ? 128 : (g == 1 ? 512 : 2048);
;                             if (isS) dst = out + (g == 0 ? O_SKV1 : (g == 1 ? O_SKV2 : O_SKV3)) + ((size_t)(l * 32 + (sq - 16)) * 8 + t) * 1024 + kv * 512 + ci;
;                             else if (t >= SEQ - keep) dst = out + (g == 0 ? O_PKV1 : (g == 1 ? O_PKV2 : O_PKV3)) + ((size_t)(l * 16 + sq) * keep + (t - (SEQ - keep))) * 1024 + kv * 512 + ci;
.LBB0_3109:
	v_and_b32_e32 v58, 0x7ef, v56
	v_cndmask_b32_e64 v52, v58, v161, s[14:15]
	v_lshl_add_u64 v[50:51], s[54:55], 0, v[56:57]
	v_cndmask_b32_e64 v53, v194, 5, s[14:15]
	v_lshlrev_b64 v[50:51], 9, v[50:51]
	v_sub_co_u32_e32 v158, vcc, v52, v53
	s_xor_b64 s[56:57], vcc, -1
	s_andn2_b64 vcc, exec, s[16:17]
	v_lshl_add_u64 v[50:51], s[22:23], 0, v[50:51]
	s_cbranch_vccnz .LBB0_3122
	v_mov_b32_e32 v147, v159
	v_lshl_add_u64 v[52:53], v[50:51], 0, v[146:147]
	s_cmp_lt_i32 s47, 1
	v_cvt_pk_bf16_f32 v62, v46, v47
	v_cvt_pk_bf16_f32 v63, v48, v49
	v_cvt_pk_bf16_f32 v64, v42, v43
	v_cvt_pk_bf16_f32 v65, v44, v45
	ds_bpermute_b32 v234, v232, v52
	ds_bpermute_b32 v235, v232, v53
	ds_bpermute_b32 v236, v232, v62
	ds_bpermute_b32 v237, v232, v63
	ds_bpermute_b32 v238, v232, v64
	ds_bpermute_b32 v239, v232, v65
	s_waitcnt lgkmcnt(0)
	global_store_dwordx4 v[234:235], v[236:239], off
	s_cbranch_scc1 .LBB0_3122
	s_cmp_lg_u32 s47, 1
	s_mov_b64 s[16:17], -1
	s_cbranch_scc0 .LBB0_3299
	v_mov_b64_e32 v[52:53], 0
	s_and_saveexec_b64 s[16:17], s[56:57]
	s_cbranch_execz .LBB0_3118
	v_mov_b32_e32 v52, s33
	v_cndmask_b32_e64 v52, v52, v60, s[14:15]
	v_cndmask_b32_e64 v53, 16, 32, s[14:15]
	v_add_u32_e32 v52, v53, v52
	v_cmp_lt_i32_e32 vcc, s96, v174
	v_mad_i64_i32 v[56:57], s[18:19], v52, 3, v[158:159]
	s_and_saveexec_b64 s[18:19], vcc
	s_xor_b64 s[18:19], exec, s[18:19]
	s_cbranch_execz .LBB0_3115
	v_lshlrev_b64 v[56:57], 12, v[56:57]
	v_cndmask_b32_e64 v52, v195, v196, s[14:15]
	v_mov_b32_e32 v53, v159
	v_lshl_add_u64 v[56:57], s[24:25], 0, v[56:57]
	v_lshl_add_u64 v[52:53], v[56:57], 0, v[52:53]
	v_mov_b32_e32 v56, v174
	v_mov_b32_e32 v57, v159
	s_movk_i32 s20, 0x9000
	v_lshl_add_u64 v[52:53], v[56:57], 2, v[52:53]
	s_mov_b32 s21, -1
	v_lshl_add_u64 v[52:53], v[52:53], 0, s[20:21]

; __device__ __forceinline__ unsigned cvt_pk_bf16(float lo, float hi) { unsigned r; asm volatile("v_cvt_pk_bf16_f32 %0, %1, %2" : "=v"(r) : "v"(lo), "v"(hi)); return r; }
;     __device__ __forceinline__ void operator()(AccT acc, const Unit& u, int wr, int wc, int fr, int fq) const {
;     ...
;             for (int bj = 0; bj < 2; ++bj) { const int c = col0 + bj * HALF;
;                 const f32x4 v0 = acc[ai][bj][m][0] * rs + sh[bj][0], v1 = acc[ai][bj][m][1] * rs + sh[bj][1];
;                 if (u.pn < 48) {
;                     u32x4 w; w.x = cvt_pk_bf16(v0[0], v0[1]); w.y = cvt_pk_bf16(v0[2], v0[3]); w.z = cvt_pk_bf16(v1[0], v1[1]); w.w = cvt_pk_bf16(v1[2], v1[3]);
;                     *(u32x4*)ZP(Z, row, c) = w;
;                     if (side) {
;                         float* dst = nullptr;
;                         if (side == 1) {
;                             const int kv = c >= ZV ? 1 : 0, cc = c - (kv ? ZV : ZK), g = cc >> 9, ci = cc & 511; const int keep = g == 0 ? 128 : (g == 1 ? 512 : 2048);
;                             if (isS) dst = out + (g == 0 ? O_SKV1 : (g == 1 ? O_SKV2 : O_SKV3)) + ((size_t)(l * 32 + (sq - 16)) * 8 + t) * 1024 + kv * 512 + ci;
;                             else if (t >= SEQ - keep) dst = out + (g == 0 ? O_PKV1 : (g == 1 ? O_PKV2 : O_PKV3)) + ((size_t)(l * 16 + sq) * keep + (t - (SEQ - keep))) * 1024 + kv * 512 + ci;
.LBB0_3122:
	s_and_b64 vcc, exec, s[8:9]
	s_cbranch_vccnz .LBB0_3135
	v_mov_b32_e32 v55, v54
	v_mov_b32_e32 v42, v54
	v_mov_b32_e32 v43, v54
	v_mov_b32_e32 v139, v159
	v_pk_fma_f32 v[32:33], v[32:33], v[42:43], v[16:17]
	v_pk_fma_f32 v[30:31], v[30:31], v[54:55], v[14:15]
	v_pk_fma_f32 v[28:29], v[28:29], v[42:43], v[12:13]
	v_pk_fma_f32 v[26:27], v[26:27], v[54:55], v[10:11]
	v_lshl_add_u64 v[46:47], v[50:51], 0, v[138:139]
	s_cmp_lt_i32 s47, 1
	v_cvt_pk_bf16_f32 v42, v30, v31
	v_cvt_pk_bf16_f32 v43, v32, v33
	v_cvt_pk_bf16_f32 v44, v26, v27
	v_cvt_pk_bf16_f32 v45, v28, v29
	ds_bpermute_b32 v234, v232, v46
	ds_bpermute_b32 v235, v232, v47
	ds_bpermute_b32 v236, v232, v42
	ds_bpermute_b32 v237, v232, v43
	ds_bpermute_b32 v238, v232, v44
	ds_bpermute_b32 v239, v232, v45
	s_waitcnt lgkmcnt(0)
	global_store_dwordx4 v[234:235], v[236:239], off
	s_cbranch_scc1 .LBB0_3135
	s_cmp_lg_u32 s47, 1
	s_mov_b64 s[16:17], -1
	s_cbranch_scc0 .LBB0_3307
	v_mov_b64_e32 v[42:43], 0
	s_and_saveexec_b64 s[16:17], s[56:57]
	s_cbranch_execz .LBB0_3131
	v_mov_b32_e32 v42, s33
	v_cndmask_b32_e64 v42, v42, v60, s[14:15]
	v_cndmask_b32_e64 v43, 16, 32, s[14:15]
	v_add_u32_e32 v42, v43, v42
	v_cmp_lt_i32_e32 vcc, s96, v144
	v_mad_i64_i32 v[44:45], s[18:19], v42, 3, v[158:159]
	s_and_saveexec_b64 s[18:19], vcc
	s_xor_b64 s[18:19], exec, s[18:19]
	v_lshlrev_b64 v[42:43], 12, v[44:45]
	v_cndmask_b32_e64 v158, v195, v196, s[14:15]
	v_lshl_add_u64 v[42:43], s[24:25], 0, v[42:43]
	v_lshl_add_u64 v[42:43], v[42:43], 0, v[158:159]
	v_mov_b32_e32 v158, v174
	v_lshl_add_u64 v[42:43], v[158:159], 2, v[42:43]
	v_lshl_add_u64 v[42:43], v[42:43], 0, s[42:43]
	s_andn2_saveexec_b64 s[18:19], s[18:19]
	s_cbranch_execz .LBB0_3130
	v_mov_b64_e32 v[42:43], s[24:25]
	v_cndmask_b32_e64 v158, v197, v198, s[14:15]
	v_mad_u64_u32 v[42:43], s[14:15], v44, s97, v[42:43]
	v_mov_b32_e32 v44, v43
	v_mad_u64_u32 v[44:45], s[14:15], v45, s97, v[44:45]
	v_mov_b32_e32 v43, v44
	v_lshl_add_u64 v[42:43], v[42:43], 0, v[158:159]
	v_ashrrev_i32_e32 v45, 31, v174
	v_mov_b32_e32 v44, v174
	v_lshl_add_u64 v[42:43], v[44:45], 2, v[42:43]
	v_lshl_add_u64 v[42:43], v[42:43], 0, s[44:45]

; __device__ __forceinline__ unsigned cvt_pk_bf16(float lo, float hi) { unsigned r; asm volatile("v_cvt_pk_bf16_f32 %0, %1, %2" : "=v"(r) : "v"(lo), "v"(hi)); return r; }
;     __device__ __forceinline__ void operator()(AccT acc, const Unit& u, int wr, int wc, int fr, int fq) const {
;     ...
;             const int sq = seq_of_row(row); const bool isS = row >= NPROMPT; const int t = isS ? ((row - NPROMPT) & 7) : (row & (SEQ - 1));
;             if (!uni) { const float* sw = SHW + (size_t)sq * NZT + col0;
; #pragma unroll
;                 for (int bj = 0; bj < 2; ++bj) { sh[bj][0] = *(const f32x4*)(sw + bj * HALF); sh[bj][1] = *(const f32x4*)(sw + bj * HALF + 4); }
;                 asm volatile("" :: "v"(sh[0][0]), "v"(sh[0][1]), "v"(sh[1][0]), "v"(sh[1][1])); }
; #pragma unroll
;             for (int bj = 0; bj < 2; ++bj) { const int c = col0 + bj * HALF;
;                 const f32x4 v0 = acc[ai][bj][m][0] * rs + sh[bj][0], v1 = acc[ai][bj][m][1] * rs + sh[bj][1];
;                 if (u.pn < 48) {
;                     u32x4 w; w.x = cvt_pk_bf16(v0[0], v0[1]); w.y = cvt_pk_bf16(v0[2], v0[3]); w.z = cvt_pk_bf16(v1[0], v1[1]); w.w = cvt_pk_bf16(v1[2], v1[3]);
;                     *(u32x4*)ZP(Z, row, c) = w;
;                     if (side) {
;                         float* dst = nullptr;
;                         if (side == 1) {
;                             const int kv = c >= ZV ? 1 : 0, cc = c - (kv ? ZV : ZK), g = cc >> 9, ci = cc & 511; const int keep = g == 0 ? 128 : (g == 1 ? 512 : 2048);
;                             if (isS) dst = out + (g == 0 ? O_SKV1 : (g == 1 ? O_SKV2 : O_SKV3)) + ((size_t)(l * 32 + (sq - 16)) * 8 + t) * 1024 + kv * 512 + ci;
;                             else if (t >= SEQ - keep) dst = out + (g == 0 ? O_PKV1 : (g == 1 ? O_PKV2 : O_PKV3)) + ((size_t)(l * 16 + sq) * keep + (t - (SEQ - keep))) * 1024 + kv * 512 + ci;
.LBB0_3173:
	v_and_b32_e32 v34, 0x7ff, v32
	v_cndmask_b32_e64 v28, v34, v161, s[12:13]
	v_lshl_add_u64 v[26:27], s[54:55], 0, v[32:33]
	v_cndmask_b32_e64 v29, v194, 5, s[12:13]
	v_lshlrev_b64 v[26:27], 9, v[26:27]
	v_sub_co_u32_e32 v158, vcc, v28, v29
	s_xor_b64 s[18:19], vcc, -1
	s_andn2_b64 vcc, exec, s[14:15]
	v_lshl_add_u64 v[26:27], s[22:23], 0, v[26:27]
	s_cbranch_vccnz .LBB0_3186
	v_mov_b32_e32 v147, v159
	v_lshl_add_u64 v[28:29], v[26:27], 0, v[146:147]
	s_cmp_lt_i32 s47, 1
	v_cvt_pk_bf16_f32 v36, v22, v23
	v_cvt_pk_bf16_f32 v37, v24, v25
	v_cvt_pk_bf16_f32 v38, v18, v19
	v_cvt_pk_bf16_f32 v39, v20, v21
	ds_bpermute_b32 v234, v232, v28
	ds_bpermute_b32 v235, v232, v29
	ds_bpermute_b32 v236, v232, v36
	ds_bpermute_b32 v237, v232, v37
	ds_bpermute_b32 v238, v232, v38
	ds_bpermute_b32 v239, v232, v39
	s_waitcnt lgkmcnt(0)
	global_store_dwordx4 v[234:235], v[236:239], off
	s_cbranch_scc1 .LBB0_3186
	s_cmp_lg_u32 s47, 1
	s_mov_b64 s[10:11], -1
	s_cbranch_scc0 .LBB0_3315
	v_mov_b64_e32 v[28:29], 0
	s_and_saveexec_b64 s[10:11], s[18:19]
	s_cbranch_execz .LBB0_3182
	v_mov_b32_e32 v28, s33
	v_cndmask_b32_e64 v28, v28, v42, s[12:13]
	v_cndmask_b32_e64 v29, 16, 32, s[12:13]
	v_add_u32_e32 v28, v29, v28
	v_cmp_lt_i32_e32 vcc, s96, v174
	v_mad_i64_i32 v[32:33], s[14:15], v28, 3, v[158:159]
	s_and_saveexec_b64 s[14:15], vcc
	s_xor_b64 s[14:15], exec, s[14:15]
	s_cbranch_execz .LBB0_3179
	v_lshlrev_b64 v[32:33], 12, v[32:33]
	v_cndmask_b32_e64 v28, v195, v196, s[12:13]
	v_mov_b32_e32 v29, v159
	v_lshl_add_u64 v[32:33], s[24:25], 0, v[32:33]
	v_lshl_add_u64 v[28:29], v[32:33], 0, v[28:29]
	v_mov_b32_e32 v175, v159
	s_movk_i32 s16, 0x9000
	v_lshl_add_u64 v[28:29], v[174:175], 2, v[28:29]
	s_mov_b32 s17, -1
	v_lshl_add_u64 v[28:29], v[28:29], 0, s[16:17]

; __device__ __forceinline__ unsigned cvt_pk_bf16(float lo, float hi) { unsigned r; asm volatile("v_cvt_pk_bf16_f32 %0, %1, %2" : "=v"(r) : "v"(lo), "v"(hi)); return r; }
;     __device__ __forceinline__ void operator()(AccT acc, const Unit& u, int wr, int wc, int fr, int fq) const {
;     ...
;             for (int bj = 0; bj < 2; ++bj) { const int c = col0 + bj * HALF;
;                 const f32x4 v0 = acc[ai][bj][m][0] * rs + sh[bj][0], v1 = acc[ai][bj][m][1] * rs + sh[bj][1];
;                 if (u.pn < 48) {
;                     u32x4 w; w.x = cvt_pk_bf16(v0[0], v0[1]); w.y = cvt_pk_bf16(v0[2], v0[3]); w.z = cvt_pk_bf16(v1[0], v1[1]); w.w = cvt_pk_bf16(v1[2], v1[3]);
;                     *(u32x4*)ZP(Z, row, c) = w;
;                     if (side) {
;                         float* dst = nullptr;
;                         if (side == 1) {
;                             const int kv = c >= ZV ? 1 : 0, cc = c - (kv ? ZV : ZK), g = cc >> 9, ci = cc & 511; const int keep = g == 0 ? 128 : (g == 1 ? 512 : 2048);
;                             if (isS) dst = out + (g == 0 ? O_SKV1 : (g == 1 ? O_SKV2 : O_SKV3)) + ((size_t)(l * 32 + (sq - 16)) * 8 + t) * 1024 + kv * 512 + ci;
;                             else if (t >= SEQ - keep) dst = out + (g == 0 ? O_PKV1 : (g == 1 ? O_PKV2 : O_PKV3)) + ((size_t)(l * 16 + sq) * keep + (t - (SEQ - keep))) * 1024 + kv * 512 + ci;
.LBB0_3186:
	s_and_b64 vcc, exec, s[8:9]
	s_cbranch_vccnz .LBB0_3199
	v_mov_b32_e32 v31, v30
	v_mov_b32_e32 v18, v30
	v_mov_b32_e32 v19, v30
	v_mov_b32_e32 v139, v159
	v_pk_fma_f32 v[8:9], v[8:9], v[18:19], v[16:17]
	v_pk_fma_f32 v[6:7], v[6:7], v[30:31], v[14:15]
	v_pk_fma_f32 v[4:5], v[4:5], v[18:19], v[12:13]
	v_pk_fma_f32 v[2:3], v[2:3], v[30:31], v[10:11]
	v_lshl_add_u64 v[14:15], v[26:27], 0, v[138:139]
	s_cmp_lt_i32 s47, 1
	v_cvt_pk_bf16_f32 v10, v6, v7
	v_cvt_pk_bf16_f32 v11, v8, v9
	v_cvt_pk_bf16_f32 v12, v2, v3
	v_cvt_pk_bf16_f32 v13, v4, v5
	ds_bpermute_b32 v234, v232, v14
	ds_bpermute_b32 v235, v232, v15
	ds_bpermute_b32 v236, v232, v10
	ds_bpermute_b32 v237, v232, v11
	ds_bpermute_b32 v238, v232, v12
	ds_bpermute_b32 v239, v232, v13
	s_waitcnt lgkmcnt(0)
	global_store_dwordx4 v[234:235], v[236:239], off
	s_cbranch_scc1 .LBB0_3199
	s_cmp_lg_u32 s47, 1
	s_mov_b64 s[8:9], -1
	s_cbranch_scc0 .LBB0_3323
	v_mov_b64_e32 v[10:11], 0
	s_and_saveexec_b64 s[8:9], s[18:19]
	s_cbranch_execz .LBB0_3195
	v_mov_b32_e32 v10, s33
	v_cndmask_b32_e64 v10, v10, v42, s[12:13]
	v_cndmask_b32_e64 v11, 16, 32, s[12:13]
	v_add_u32_e32 v10, v11, v10
	v_cmp_lt_i32_e32 vcc, s96, v144
	v_mad_i64_i32 v[12:13], s[10:11], v10, 3, v[158:159]
	s_and_saveexec_b64 s[10:11], vcc
	s_xor_b64 s[10:11], exec, s[10:11]
	v_lshlrev_b64 v[10:11], 12, v[12:13]
	v_cndmask_b32_e64 v158, v195, v196, s[12:13]
	v_lshl_add_u64 v[10:11], s[24:25], 0, v[10:11]
	v_lshl_add_u64 v[10:11], v[10:11], 0, v[158:159]
	v_mov_b32_e32 v175, v159
	v_lshl_add_u64 v[10:11], v[174:175], 2, v[10:11]
	v_lshl_add_u64 v[10:11], v[10:11], 0, s[42:43]
	s_andn2_saveexec_b64 s[10:11], s[10:11]
	s_cbranch_execz .LBB0_3194
	v_mov_b64_e32 v[10:11], s[24:25]
	v_cndmask_b32_e64 v158, v197, v198, s[12:13]
	v_mad_u64_u32 v[10:11], s[12:13], v12, s97, v[10:11]
	v_mov_b32_e32 v12, v11
	v_mad_u64_u32 v[12:13], s[12:13], v13, s97, v[12:13]
	v_mov_b32_e32 v11, v12
	v_lshl_add_u64 v[10:11], v[10:11], 0, v[158:159]
	v_ashrrev_i32_e32 v175, 31, v174
	v_lshl_add_u64 v[10:11], v[174:175], 2, v[10:11]
	v_lshl_add_u64 v[10:11], v[10:11], 0, s[44:45]
